# GDN part-A forward substitution: LDS reads software-pipelined 12 deep (counted lgkmcnt) instead of read-wait-fma serial chain
# speedup vs baseline: 1.0460x; 1.0460x over previous
.LBB0_933:
	v_cmp_gt_i32_e32 vcc, s27, v80
	s_waitcnt lgkmcnt(0)
	s_barrier
	s_and_saveexec_b64 s[0:1], vcc
	s_xor_b64 s[0:1], exec, s[0:1]
	s_cbranch_execz .LBB0_939
	v_lshl_add_u32 v1, v80, 2, 0
	v_add_u32_e32 v1, 0xca00, v1
	ds_read_b32 v0, v1 offset:0
	ds_read2st64_b32 v[4:5], v1 offset0:4 offset1:8
	ds_read2st64_b32 v[6:7], v1 offset0:12 offset1:16
	ds_read2st64_b32 v[8:9], v1 offset0:20 offset1:24
	ds_read2st64_b32 v[10:11], v1 offset0:28 offset1:32
	ds_read2st64_b32 v[12:13], v1 offset0:36 offset1:40
	ds_read2st64_b32 v[14:15], v1 offset0:44 offset1:48
	ds_read2st64_b32 v[16:17], v1 offset0:52 offset1:56
	ds_read_b32 v18, v1 offset:15360
	ds_read2st64_b32 v[20:21], v1 offset0:64 offset1:68
	ds_read2st64_b32 v[22:23], v1 offset0:72 offset1:76
	ds_read2st64_b32 v[24:25], v1 offset0:80 offset1:84
	ds_read2st64_b32 v[26:27], v1 offset0:88 offset1:92
	ds_read2st64_b32 v[28:29], v1 offset0:96 offset1:100
	ds_read2st64_b32 v[30:31], v1 offset0:104 offset1:108
	ds_read2st64_b32 v[32:33], v1 offset0:112 offset1:116
	ds_read2st64_b32 v[34:35], v1 offset0:120 offset1:124
	ds_read2st64_b32 v[36:37], v1 offset0:128 offset1:132
	ds_read2st64_b32 v[38:39], v1 offset0:136 offset1:140
	ds_read2st64_b32 v[40:41], v1 offset0:144 offset1:148
	ds_read2st64_b32 v[42:43], v1 offset0:152 offset1:156
	ds_read2st64_b32 v[44:45], v1 offset0:160 offset1:164
	ds_read2st64_b32 v[46:47], v1 offset0:168 offset1:172
	ds_read2st64_b32 v[48:49], v1 offset0:176 offset1:180
	ds_read2st64_b32 v[50:51], v1 offset0:184 offset1:188
	ds_read2st64_b32 v[52:53], v1 offset0:192 offset1:196
	ds_read2st64_b32 v[54:55], v1 offset0:200 offset1:204
	ds_read2st64_b32 v[56:57], v1 offset0:208 offset1:212
	ds_read2st64_b32 v[58:59], v1 offset0:216 offset1:220
	ds_read2st64_b32 v[60:61], v1 offset0:224 offset1:228
	ds_read2st64_b32 v[62:63], v1 offset0:232 offset1:236
	ds_read2st64_b32 v[64:65], v1 offset0:240 offset1:244
	ds_read2st64_b32 v[2:3], v1 offset0:248 offset1:252
	ds_read_b128 v[136:139], v105 offset:35584
	ds_read_b128 v[140:143], v105 offset:35840
	ds_read_b128 v[144:147], v105 offset:36096
	ds_read_b128 v[148:151], v105 offset:36352
	ds_read_b128 v[152:155], v105 offset:36608
	ds_read_b128 v[156:159], v105 offset:36624
	ds_read_b128 v[160:163], v105 offset:36864
	ds_read_b128 v[164:167], v105 offset:36880
	ds_read_b128 v[168:171], v105 offset:37120
	ds_read_b128 v[172:175], v105 offset:37136
	ds_read_b128 v[176:179], v105 offset:37376
	ds_read_b128 v[180:183], v105 offset:37392
	s_waitcnt lgkmcnt(11)
	v_mul_f32_e32 v66, v136, v0
	v_sub_f32_e32 v4, v4, v66
	ds_read_b128 v[136:139], v105 offset:37632
	s_waitcnt lgkmcnt(11)
	v_mul_f32_e32 v66, v140, v0
	v_mul_f32_e32 v67, v141, v4
	v_sub_f32_e32 v5, v5, v66
	v_sub_f32_e32 v5, v5, v67
	ds_read_b128 v[140:143], v105 offset:37648
	s_waitcnt lgkmcnt(11)
	v_mul_f32_e32 v66, v144, v0
	v_mul_f32_e32 v67, v145, v4
	v_fmac_f32_e32 v66, v146, v5
	v_sub_f32_e32 v6, v6, v66
	v_sub_f32_e32 v6, v6, v67
	ds_read_b128 v[144:147], v105 offset:37664
	s_waitcnt lgkmcnt(11)
	v_mul_f32_e32 v66, v148, v0
	v_mul_f32_e32 v67, v149, v4
	v_fmac_f32_e32 v66, v150, v5
	v_fmac_f32_e32 v67, v151, v6
	v_sub_f32_e32 v7, v7, v66
	v_sub_f32_e32 v7, v7, v67
	ds_read_b128 v[148:151], v105 offset:37888
	s_waitcnt lgkmcnt(11)
	v_mul_f32_e32 v66, v152, v0
	v_mul_f32_e32 v67, v153, v4
	v_fmac_f32_e32 v66, v154, v5
	v_fmac_f32_e32 v67, v155, v6
	ds_read_b128 v[152:155], v105 offset:37904
	s_waitcnt lgkmcnt(11)
	v_fmac_f32_e32 v66, v156, v7
	v_sub_f32_e32 v8, v8, v66
	v_sub_f32_e32 v8, v8, v67
	ds_read_b128 v[156:159], v105 offset:37920
	s_waitcnt lgkmcnt(11)
	v_mul_f32_e32 v66, v160, v0
	v_mul_f32_e32 v67, v161, v4
	v_fmac_f32_e32 v66, v162, v5
	v_fmac_f32_e32 v67, v163, v6
	ds_read_b128 v[160:163], v105 offset:38144
	s_waitcnt lgkmcnt(11)
	v_fmac_f32_e32 v66, v164, v7
	v_fmac_f32_e32 v67, v165, v8
	v_sub_f32_e32 v9, v9, v66
	v_sub_f32_e32 v9, v9, v67
	ds_read_b128 v[164:167], v105 offset:38160
	s_waitcnt lgkmcnt(11)
	v_mul_f32_e32 v66, v168, v0
	v_mul_f32_e32 v67, v169, v4
	v_fmac_f32_e32 v66, v170, v5
	v_fmac_f32_e32 v67, v171, v6
	ds_read_b128 v[168:171], v105 offset:38176
	s_waitcnt lgkmcnt(11)
	v_fmac_f32_e32 v66, v172, v7
	v_fmac_f32_e32 v67, v173, v8
	v_fmac_f32_e32 v66, v174, v9
	v_sub_f32_e32 v10, v10, v66
	v_sub_f32_e32 v10, v10, v67
	ds_read_b128 v[172:175], v105 offset:38400
	s_waitcnt lgkmcnt(11)
	v_mul_f32_e32 v66, v176, v0
	v_mul_f32_e32 v67, v177, v4
	v_fmac_f32_e32 v66, v178, v5
	v_fmac_f32_e32 v67, v179, v6
	ds_read_b128 v[176:179], v105 offset:38416
	s_waitcnt lgkmcnt(11)
	v_fmac_f32_e32 v66, v180, v7
	v_fmac_f32_e32 v67, v181, v8
	v_fmac_f32_e32 v66, v182, v9
	v_fmac_f32_e32 v67, v183, v10
	v_sub_f32_e32 v11, v11, v66
	v_sub_f32_e32 v11, v11, v67
	ds_read_b128 v[180:183], v105 offset:38432
	s_waitcnt lgkmcnt(11)
	v_mul_f32_e32 v66, v136, v0
	v_mul_f32_e32 v67, v137, v4
	v_fmac_f32_e32 v66, v138, v5
	v_fmac_f32_e32 v67, v139, v6
	ds_read_b128 v[136:139], v105 offset:38656
	s_waitcnt lgkmcnt(11)
	v_fmac_f32_e32 v66, v140, v7
	v_fmac_f32_e32 v67, v141, v8
	v_fmac_f32_e32 v66, v142, v9
	v_fmac_f32_e32 v67, v143, v10
	ds_read_b128 v[140:143], v105 offset:38672
	s_waitcnt lgkmcnt(11)
	v_fmac_f32_e32 v66, v144, v11
	v_sub_f32_e32 v12, v12, v66
	v_sub_f32_e32 v12, v12, v67
	ds_read_b128 v[144:147], v105 offset:38688
	s_waitcnt lgkmcnt(11)
	v_mul_f32_e32 v66, v148, v0
	v_mul_f32_e32 v67, v149, v4
	v_fmac_f32_e32 v66, v150, v5
	v_fmac_f32_e32 v67, v151, v6
	ds_read_b128 v[148:151], v105 offset:38704
	s_waitcnt lgkmcnt(11)
	v_fmac_f32_e32 v66, v152, v7
	v_fmac_f32_e32 v67, v153, v8
	v_fmac_f32_e32 v66, v154, v9
	v_fmac_f32_e32 v67, v155, v10
	ds_read_b128 v[152:155], v105 offset:38912
	s_waitcnt lgkmcnt(11)
	v_fmac_f32_e32 v66, v156, v11
	v_fmac_f32_e32 v67, v157, v12
	v_sub_f32_e32 v13, v13, v66
	v_sub_f32_e32 v13, v13, v67
	ds_read_b128 v[156:159], v105 offset:38928
	s_waitcnt lgkmcnt(11)
	v_mul_f32_e32 v66, v160, v0
	v_mul_f32_e32 v67, v161, v4
	v_fmac_f32_e32 v66, v162, v5
	v_fmac_f32_e32 v67, v163, v6
	ds_read_b128 v[160:163], v105 offset:38944
	s_waitcnt lgkmcnt(11)
	v_fmac_f32_e32 v66, v164, v7
	v_fmac_f32_e32 v67, v165, v8
	v_fmac_f32_e32 v66, v166, v9
	v_fmac_f32_e32 v67, v167, v10
	ds_read_b128 v[164:167], v105 offset:38960
	s_waitcnt lgkmcnt(11)
	v_fmac_f32_e32 v66, v168, v11
	v_fmac_f32_e32 v67, v169, v12
	v_fmac_f32_e32 v66, v170, v13
	v_sub_f32_e32 v14, v14, v66
	v_sub_f32_e32 v14, v14, v67
	ds_read_b128 v[168:171], v105 offset:39168
	s_waitcnt lgkmcnt(11)
	v_mul_f32_e32 v66, v172, v0
	v_mul_f32_e32 v67, v173, v4
	v_fmac_f32_e32 v66, v174, v5
	v_fmac_f32_e32 v67, v175, v6
	ds_read_b128 v[172:175], v105 offset:39184
	s_waitcnt lgkmcnt(11)
	v_fmac_f32_e32 v66, v176, v7
	v_fmac_f32_e32 v67, v177, v8
	v_fmac_f32_e32 v66, v178, v9
	v_fmac_f32_e32 v67, v179, v10
	ds_read_b128 v[176:179], v105 offset:39200
	s_waitcnt lgkmcnt(11)
	v_fmac_f32_e32 v66, v180, v11
	v_fmac_f32_e32 v67, v181, v12
	v_fmac_f32_e32 v66, v182, v13
	v_fmac_f32_e32 v67, v183, v14
	v_sub_f32_e32 v15, v15, v66
	v_sub_f32_e32 v15, v15, v67
	ds_read_b128 v[180:183], v105 offset:39216
	s_waitcnt lgkmcnt(11)
	v_mul_f32_e32 v66, v136, v0
	v_mul_f32_e32 v67, v137, v4
	v_fmac_f32_e32 v66, v138, v5
	v_fmac_f32_e32 v67, v139, v6
	ds_read_b128 v[136:139], v105 offset:39424
	s_waitcnt lgkmcnt(11)
	v_fmac_f32_e32 v66, v140, v7
	v_fmac_f32_e32 v67, v141, v8
	v_fmac_f32_e32 v66, v142, v9
	v_fmac_f32_e32 v67, v143, v10
	ds_read_b128 v[140:143], v105 offset:39440
	s_waitcnt lgkmcnt(11)
	v_fmac_f32_e32 v66, v144, v11
	v_fmac_f32_e32 v67, v145, v12
	v_fmac_f32_e32 v66, v146, v13
	v_fmac_f32_e32 v67, v147, v14
	ds_read_b128 v[144:147], v105 offset:39456
	s_waitcnt lgkmcnt(11)
	v_fmac_f32_e32 v66, v148, v15
	v_sub_f32_e32 v16, v16, v66
	v_sub_f32_e32 v16, v16, v67
	ds_read_b128 v[148:151], v105 offset:39472
	s_waitcnt lgkmcnt(11)
	v_mul_f32_e32 v66, v152, v0
	v_mul_f32_e32 v67, v153, v4
	v_fmac_f32_e32 v66, v154, v5
	v_fmac_f32_e32 v67, v155, v6
	ds_read_b128 v[152:155], v105 offset:39680
	s_waitcnt lgkmcnt(11)
	v_fmac_f32_e32 v66, v156, v7
	v_fmac_f32_e32 v67, v157, v8
	v_fmac_f32_e32 v66, v158, v9
	v_fmac_f32_e32 v67, v159, v10
	ds_read_b128 v[156:159], v105 offset:39696
	s_waitcnt lgkmcnt(11)
	v_fmac_f32_e32 v66, v160, v11
	v_fmac_f32_e32 v67, v161, v12
	v_fmac_f32_e32 v66, v162, v13
	v_fmac_f32_e32 v67, v163, v14
	ds_read_b128 v[160:163], v105 offset:39712
	s_waitcnt lgkmcnt(11)
	v_fmac_f32_e32 v66, v164, v15
	v_fmac_f32_e32 v67, v165, v16
	v_sub_f32_e32 v17, v17, v66
	v_sub_f32_e32 v17, v17, v67
	ds_read_b128 v[164:167], v105 offset:39728
	s_waitcnt lgkmcnt(11)
	v_mul_f32_e32 v66, v168, v0
	v_mul_f32_e32 v67, v169, v4
	v_fmac_f32_e32 v66, v170, v5
	v_fmac_f32_e32 v67, v171, v6
	ds_read_b128 v[168:171], v105 offset:39744
	s_waitcnt lgkmcnt(11)
	v_fmac_f32_e32 v66, v172, v7
	v_fmac_f32_e32 v67, v173, v8
	v_fmac_f32_e32 v66, v174, v9
	v_fmac_f32_e32 v67, v175, v10
	ds_read_b128 v[172:175], v105 offset:39936
	s_waitcnt lgkmcnt(11)
	v_fmac_f32_e32 v66, v176, v11
	v_fmac_f32_e32 v67, v177, v12
	v_fmac_f32_e32 v66, v178, v13
	v_fmac_f32_e32 v67, v179, v14
	ds_read_b128 v[176:179], v105 offset:39952
	s_waitcnt lgkmcnt(11)
	v_fmac_f32_e32 v66, v180, v15
	v_fmac_f32_e32 v67, v181, v16
	v_fmac_f32_e32 v66, v182, v17
	v_sub_f32_e32 v18, v18, v66
	v_sub_f32_e32 v18, v18, v67
	ds_read_b128 v[180:183], v105 offset:39968
	s_waitcnt lgkmcnt(11)
	v_mul_f32_e32 v66, v136, v0
	v_mul_f32_e32 v67, v137, v4
	v_fmac_f32_e32 v66, v138, v5
	v_fmac_f32_e32 v67, v139, v6
	ds_read_b128 v[136:139], v105 offset:39984
	s_waitcnt lgkmcnt(11)
	v_fmac_f32_e32 v66, v140, v7
	v_fmac_f32_e32 v67, v141, v8
	v_fmac_f32_e32 v66, v142, v9
	v_fmac_f32_e32 v67, v143, v10
	ds_read_b128 v[140:143], v105 offset:40000
	s_waitcnt lgkmcnt(11)
	v_fmac_f32_e32 v66, v144, v11
	v_fmac_f32_e32 v67, v145, v12
	v_fmac_f32_e32 v66, v146, v13
	v_fmac_f32_e32 v67, v147, v14
	ds_read_b128 v[144:147], v105 offset:40192
	s_waitcnt lgkmcnt(11)
	v_fmac_f32_e32 v66, v148, v15
	v_fmac_f32_e32 v67, v149, v16
	v_fmac_f32_e32 v66, v150, v17
	v_fmac_f32_e32 v67, v151, v18
	v_sub_f32_e32 v20, v20, v66
	v_sub_f32_e32 v20, v20, v67
	ds_read_b128 v[148:151], v105 offset:40208
	s_waitcnt lgkmcnt(11)
	v_mul_f32_e32 v66, v152, v0
	v_mul_f32_e32 v67, v153, v4
	v_fmac_f32_e32 v66, v154, v5
	v_fmac_f32_e32 v67, v155, v6
	ds_read_b128 v[152:155], v105 offset:40224
	s_waitcnt lgkmcnt(11)
	v_fmac_f32_e32 v66, v156, v7
	v_fmac_f32_e32 v67, v157, v8
	v_fmac_f32_e32 v66, v158, v9
	v_fmac_f32_e32 v67, v159, v10
	ds_read_b128 v[156:159], v105 offset:40240
	s_waitcnt lgkmcnt(11)
	v_fmac_f32_e32 v66, v160, v11
	v_fmac_f32_e32 v67, v161, v12
	v_fmac_f32_e32 v66, v162, v13
	v_fmac_f32_e32 v67, v163, v14
	ds_read_b128 v[160:163], v105 offset:40256
	s_waitcnt lgkmcnt(11)
	v_fmac_f32_e32 v66, v164, v15
	v_fmac_f32_e32 v67, v165, v16
	v_fmac_f32_e32 v66, v166, v17
	v_fmac_f32_e32 v67, v167, v18
	ds_read_b128 v[164:167], v105 offset:40448
	s_waitcnt lgkmcnt(11)
	v_fmac_f32_e32 v66, v168, v20
	v_sub_f32_e32 v21, v21, v66
	v_sub_f32_e32 v21, v21, v67
	ds_read_b128 v[168:171], v105 offset:40464
	s_waitcnt lgkmcnt(11)
	v_mul_f32_e32 v66, v172, v0
	v_mul_f32_e32 v67, v173, v4
	v_fmac_f32_e32 v66, v174, v5
	v_fmac_f32_e32 v67, v175, v6
	ds_read_b128 v[172:175], v105 offset:40480
	s_waitcnt lgkmcnt(11)
	v_fmac_f32_e32 v66, v176, v7
	v_fmac_f32_e32 v67, v177, v8
	v_fmac_f32_e32 v66, v178, v9
	v_fmac_f32_e32 v67, v179, v10
	ds_read_b128 v[176:179], v105 offset:40496
	s_waitcnt lgkmcnt(11)
	v_fmac_f32_e32 v66, v180, v11
	v_fmac_f32_e32 v67, v181, v12
	v_fmac_f32_e32 v66, v182, v13
	v_fmac_f32_e32 v67, v183, v14
	ds_read_b128 v[180:183], v105 offset:40512
	s_waitcnt lgkmcnt(11)
	v_fmac_f32_e32 v66, v136, v15
	v_fmac_f32_e32 v67, v137, v16
	v_fmac_f32_e32 v66, v138, v17
	v_fmac_f32_e32 v67, v139, v18
	ds_read_b128 v[136:139], v105 offset:40704
	s_waitcnt lgkmcnt(11)
	v_fmac_f32_e32 v66, v140, v20
	v_fmac_f32_e32 v67, v141, v21
	v_sub_f32_e32 v22, v22, v66
	v_sub_f32_e32 v22, v22, v67
	ds_read_b128 v[140:143], v105 offset:40720
	s_waitcnt lgkmcnt(11)
	v_mul_f32_e32 v66, v144, v0
	v_mul_f32_e32 v67, v145, v4
	v_fmac_f32_e32 v66, v146, v5
	v_fmac_f32_e32 v67, v147, v6
	ds_read_b128 v[144:147], v105 offset:40736
	s_waitcnt lgkmcnt(11)
	v_fmac_f32_e32 v66, v148, v7
	v_fmac_f32_e32 v67, v149, v8
	v_fmac_f32_e32 v66, v150, v9
	v_fmac_f32_e32 v67, v151, v10
	ds_read_b128 v[148:151], v105 offset:40752
	s_waitcnt lgkmcnt(11)
	v_fmac_f32_e32 v66, v152, v11
	v_fmac_f32_e32 v67, v153, v12
	v_fmac_f32_e32 v66, v154, v13
	v_fmac_f32_e32 v67, v155, v14
	ds_read_b128 v[152:155], v105 offset:40768
	s_waitcnt lgkmcnt(11)
	v_fmac_f32_e32 v66, v156, v15
	v_fmac_f32_e32 v67, v157, v16
	v_fmac_f32_e32 v66, v158, v17
	v_fmac_f32_e32 v67, v159, v18
	ds_read_b128 v[156:159], v105 offset:40784
	s_waitcnt lgkmcnt(11)
	v_fmac_f32_e32 v66, v160, v20
	v_fmac_f32_e32 v67, v161, v21
	v_fmac_f32_e32 v66, v162, v22
	v_sub_f32_e32 v23, v23, v66
	v_sub_f32_e32 v23, v23, v67
	ds_read_b128 v[160:163], v105 offset:40960
	s_waitcnt lgkmcnt(11)
	v_mul_f32_e32 v66, v164, v0
	v_mul_f32_e32 v67, v165, v4
	v_fmac_f32_e32 v66, v166, v5
	v_fmac_f32_e32 v67, v167, v6
	ds_read_b128 v[164:167], v105 offset:40976
	s_waitcnt lgkmcnt(11)
	v_fmac_f32_e32 v66, v168, v7
	v_fmac_f32_e32 v67, v169, v8
	v_fmac_f32_e32 v66, v170, v9
	v_fmac_f32_e32 v67, v171, v10
	ds_read_b128 v[168:171], v105 offset:40992
	s_waitcnt lgkmcnt(11)
	v_fmac_f32_e32 v66, v172, v11
	v_fmac_f32_e32 v67, v173, v12
	v_fmac_f32_e32 v66, v174, v13
	v_fmac_f32_e32 v67, v175, v14
	ds_read_b128 v[172:175], v105 offset:41008
	s_waitcnt lgkmcnt(11)
	v_fmac_f32_e32 v66, v176, v15
	v_fmac_f32_e32 v67, v177, v16
	v_fmac_f32_e32 v66, v178, v17
	v_fmac_f32_e32 v67, v179, v18
	ds_read_b128 v[176:179], v105 offset:41024
	s_waitcnt lgkmcnt(11)
	v_fmac_f32_e32 v66, v180, v20
	v_fmac_f32_e32 v67, v181, v21
	v_fmac_f32_e32 v66, v182, v22
	v_fmac_f32_e32 v67, v183, v23
	v_sub_f32_e32 v24, v24, v66
	v_sub_f32_e32 v24, v24, v67
	ds_read_b128 v[180:183], v105 offset:41040
	s_waitcnt lgkmcnt(11)
	v_mul_f32_e32 v66, v136, v0
	v_mul_f32_e32 v67, v137, v4
	v_fmac_f32_e32 v66, v138, v5
	v_fmac_f32_e32 v67, v139, v6
	ds_read_b128 v[136:139], v105 offset:41216
	s_waitcnt lgkmcnt(11)
	v_fmac_f32_e32 v66, v140, v7
	v_fmac_f32_e32 v67, v141, v8
	v_fmac_f32_e32 v66, v142, v9
	v_fmac_f32_e32 v67, v143, v10
	ds_read_b128 v[140:143], v105 offset:41232
	s_waitcnt lgkmcnt(11)
	v_fmac_f32_e32 v66, v144, v11
	v_fmac_f32_e32 v67, v145, v12
	v_fmac_f32_e32 v66, v146, v13
	v_fmac_f32_e32 v67, v147, v14
	ds_read_b128 v[144:147], v105 offset:41248
	s_waitcnt lgkmcnt(11)
	v_fmac_f32_e32 v66, v148, v15
	v_fmac_f32_e32 v67, v149, v16
	v_fmac_f32_e32 v66, v150, v17
	v_fmac_f32_e32 v67, v151, v18
	ds_read_b128 v[148:151], v105 offset:41264
	s_waitcnt lgkmcnt(11)
	v_fmac_f32_e32 v66, v152, v20
	v_fmac_f32_e32 v67, v153, v21
	v_fmac_f32_e32 v66, v154, v22
	v_fmac_f32_e32 v67, v155, v23
	ds_read_b128 v[152:155], v105 offset:41280
	s_waitcnt lgkmcnt(11)
	v_fmac_f32_e32 v66, v156, v24
	v_sub_f32_e32 v25, v25, v66
	v_sub_f32_e32 v25, v25, v67
	ds_read_b128 v[156:159], v105 offset:41296
	s_waitcnt lgkmcnt(11)
	v_mul_f32_e32 v66, v160, v0
	v_mul_f32_e32 v67, v161, v4
	v_fmac_f32_e32 v66, v162, v5
	v_fmac_f32_e32 v67, v163, v6
	ds_read_b128 v[160:163], v105 offset:41472
	s_waitcnt lgkmcnt(11)
	v_fmac_f32_e32 v66, v164, v7
	v_fmac_f32_e32 v67, v165, v8
	v_fmac_f32_e32 v66, v166, v9
	v_fmac_f32_e32 v67, v167, v10
	ds_read_b128 v[164:167], v105 offset:41488
	s_waitcnt lgkmcnt(11)
	v_fmac_f32_e32 v66, v168, v11
	v_fmac_f32_e32 v67, v169, v12
	v_fmac_f32_e32 v66, v170, v13
	v_fmac_f32_e32 v67, v171, v14
	ds_read_b128 v[168:171], v105 offset:41504
	s_waitcnt lgkmcnt(11)
	v_fmac_f32_e32 v66, v172, v15
	v_fmac_f32_e32 v67, v173, v16
	v_fmac_f32_e32 v66, v174, v17
	v_fmac_f32_e32 v67, v175, v18
	ds_read_b128 v[172:175], v105 offset:41520
	s_waitcnt lgkmcnt(11)
	v_fmac_f32_e32 v66, v176, v20
	v_fmac_f32_e32 v67, v177, v21
	v_fmac_f32_e32 v66, v178, v22
	v_fmac_f32_e32 v67, v179, v23
	ds_read_b128 v[176:179], v105 offset:41536
	s_waitcnt lgkmcnt(11)
	v_fmac_f32_e32 v66, v180, v24
	v_fmac_f32_e32 v67, v181, v25
	v_sub_f32_e32 v26, v26, v66
	v_sub_f32_e32 v26, v26, v67
	ds_read_b128 v[180:183], v105 offset:41552
	s_waitcnt lgkmcnt(11)
	v_mul_f32_e32 v66, v136, v0
	v_mul_f32_e32 v67, v137, v4
	v_fmac_f32_e32 v66, v138, v5
	v_fmac_f32_e32 v67, v139, v6
	ds_read_b128 v[136:139], v105 offset:41728
	s_waitcnt lgkmcnt(11)
	v_fmac_f32_e32 v66, v140, v7
	v_fmac_f32_e32 v67, v141, v8
	v_fmac_f32_e32 v66, v142, v9
	v_fmac_f32_e32 v67, v143, v10
	ds_read_b128 v[140:143], v105 offset:41744
	s_waitcnt lgkmcnt(11)
	v_fmac_f32_e32 v66, v144, v11
	v_fmac_f32_e32 v67, v145, v12
	v_fmac_f32_e32 v66, v146, v13
	v_fmac_f32_e32 v67, v147, v14
	ds_read_b128 v[144:147], v105 offset:41760
	s_waitcnt lgkmcnt(11)
	v_fmac_f32_e32 v66, v148, v15
	v_fmac_f32_e32 v67, v149, v16
	v_fmac_f32_e32 v66, v150, v17
	v_fmac_f32_e32 v67, v151, v18
	ds_read_b128 v[148:151], v105 offset:41776
	s_waitcnt lgkmcnt(11)
	v_fmac_f32_e32 v66, v152, v20
	v_fmac_f32_e32 v67, v153, v21
	v_fmac_f32_e32 v66, v154, v22
	v_fmac_f32_e32 v67, v155, v23
	ds_read_b128 v[152:155], v105 offset:41792
	s_waitcnt lgkmcnt(11)
	v_fmac_f32_e32 v66, v156, v24
	v_fmac_f32_e32 v67, v157, v25
	v_fmac_f32_e32 v66, v158, v26
	v_sub_f32_e32 v27, v27, v66
	v_sub_f32_e32 v27, v27, v67
	ds_read_b128 v[156:159], v105 offset:41808
	s_waitcnt lgkmcnt(11)
	v_mul_f32_e32 v66, v160, v0
	v_mul_f32_e32 v67, v161, v4
	v_fmac_f32_e32 v66, v162, v5
	v_fmac_f32_e32 v67, v163, v6
	ds_read_b128 v[160:163], v105 offset:41824
	s_waitcnt lgkmcnt(11)
	v_fmac_f32_e32 v66, v164, v7
	v_fmac_f32_e32 v67, v165, v8
	v_fmac_f32_e32 v66, v166, v9
	v_fmac_f32_e32 v67, v167, v10
	ds_read_b128 v[164:167], v105 offset:41984
	s_waitcnt lgkmcnt(11)
	v_fmac_f32_e32 v66, v168, v11
	v_fmac_f32_e32 v67, v169, v12
	v_fmac_f32_e32 v66, v170, v13
	v_fmac_f32_e32 v67, v171, v14
	ds_read_b128 v[168:171], v105 offset:42000
	s_waitcnt lgkmcnt(11)
	v_fmac_f32_e32 v66, v172, v15
	v_fmac_f32_e32 v67, v173, v16
	v_fmac_f32_e32 v66, v174, v17
	v_fmac_f32_e32 v67, v175, v18
	ds_read_b128 v[172:175], v105 offset:42016
	s_waitcnt lgkmcnt(11)
	v_fmac_f32_e32 v66, v176, v20
	v_fmac_f32_e32 v67, v177, v21
	v_fmac_f32_e32 v66, v178, v22
	v_fmac_f32_e32 v67, v179, v23
	ds_read_b128 v[176:179], v105 offset:42032
	s_waitcnt lgkmcnt(11)
	v_fmac_f32_e32 v66, v180, v24
	v_fmac_f32_e32 v67, v181, v25
	v_fmac_f32_e32 v66, v182, v26
	v_fmac_f32_e32 v67, v183, v27
	v_sub_f32_e32 v28, v28, v66
	v_sub_f32_e32 v28, v28, v67
	ds_read_b128 v[180:183], v105 offset:42048
	s_waitcnt lgkmcnt(11)
	v_mul_f32_e32 v66, v136, v0
	v_mul_f32_e32 v67, v137, v4
	v_fmac_f32_e32 v66, v138, v5
	v_fmac_f32_e32 v67, v139, v6
	ds_read_b128 v[136:139], v105 offset:42064
	s_waitcnt lgkmcnt(11)
	v_fmac_f32_e32 v66, v140, v7
	v_fmac_f32_e32 v67, v141, v8
	v_fmac_f32_e32 v66, v142, v9
	v_fmac_f32_e32 v67, v143, v10
	ds_read_b128 v[140:143], v105 offset:42080
	s_waitcnt lgkmcnt(11)
	v_fmac_f32_e32 v66, v144, v11
	v_fmac_f32_e32 v67, v145, v12
	v_fmac_f32_e32 v66, v146, v13
	v_fmac_f32_e32 v67, v147, v14
	ds_read_b128 v[144:147], v105 offset:42240
	s_waitcnt lgkmcnt(11)
	v_fmac_f32_e32 v66, v148, v15
	v_fmac_f32_e32 v67, v149, v16
	v_fmac_f32_e32 v66, v150, v17
	v_fmac_f32_e32 v67, v151, v18
	ds_read_b128 v[148:151], v105 offset:42256
	s_waitcnt lgkmcnt(11)
	v_fmac_f32_e32 v66, v152, v20
	v_fmac_f32_e32 v67, v153, v21
	v_fmac_f32_e32 v66, v154, v22
	v_fmac_f32_e32 v67, v155, v23
	ds_read_b128 v[152:155], v105 offset:42272
	s_waitcnt lgkmcnt(11)
	v_fmac_f32_e32 v66, v156, v24
	v_fmac_f32_e32 v67, v157, v25
	v_fmac_f32_e32 v66, v158, v26
	v_fmac_f32_e32 v67, v159, v27
	ds_read_b128 v[156:159], v105 offset:42288
	s_waitcnt lgkmcnt(11)
	v_fmac_f32_e32 v66, v160, v28
	v_sub_f32_e32 v29, v29, v66
	v_sub_f32_e32 v29, v29, v67
	ds_read_b128 v[160:163], v105 offset:42304
	s_waitcnt lgkmcnt(11)
	v_mul_f32_e32 v66, v164, v0
	v_mul_f32_e32 v67, v165, v4
	v_fmac_f32_e32 v66, v166, v5
	v_fmac_f32_e32 v67, v167, v6
	ds_read_b128 v[164:167], v105 offset:42320
	s_waitcnt lgkmcnt(11)
	v_fmac_f32_e32 v66, v168, v7
	v_fmac_f32_e32 v67, v169, v8
	v_fmac_f32_e32 v66, v170, v9
	v_fmac_f32_e32 v67, v171, v10
	ds_read_b128 v[168:171], v105 offset:42336
	s_waitcnt lgkmcnt(11)
	v_fmac_f32_e32 v66, v172, v11
	v_fmac_f32_e32 v67, v173, v12
	v_fmac_f32_e32 v66, v174, v13
	v_fmac_f32_e32 v67, v175, v14
	ds_read_b128 v[172:175], v105 offset:42496
	s_waitcnt lgkmcnt(11)
	v_fmac_f32_e32 v66, v176, v15
	v_fmac_f32_e32 v67, v177, v16
	v_fmac_f32_e32 v66, v178, v17
	v_fmac_f32_e32 v67, v179, v18
	ds_read_b128 v[176:179], v105 offset:42512
	s_waitcnt lgkmcnt(11)
	v_fmac_f32_e32 v66, v180, v20
	v_fmac_f32_e32 v67, v181, v21
	v_fmac_f32_e32 v66, v182, v22
	v_fmac_f32_e32 v67, v183, v23
	ds_read_b128 v[180:183], v105 offset:42528
	s_waitcnt lgkmcnt(11)
	v_fmac_f32_e32 v66, v136, v24
	v_fmac_f32_e32 v67, v137, v25
	v_fmac_f32_e32 v66, v138, v26
	v_fmac_f32_e32 v67, v139, v27
	ds_read_b128 v[136:139], v105 offset:42544
	s_waitcnt lgkmcnt(11)
	v_fmac_f32_e32 v66, v140, v28
	v_fmac_f32_e32 v67, v141, v29
	v_sub_f32_e32 v30, v30, v66
	v_sub_f32_e32 v30, v30, v67
	ds_read_b128 v[140:143], v105 offset:42560
	s_waitcnt lgkmcnt(11)
	v_mul_f32_e32 v66, v144, v0
	v_mul_f32_e32 v67, v145, v4
	v_fmac_f32_e32 v66, v146, v5
	v_fmac_f32_e32 v67, v147, v6
	ds_read_b128 v[144:147], v105 offset:42576
	s_waitcnt lgkmcnt(11)
	v_fmac_f32_e32 v66, v148, v7
	v_fmac_f32_e32 v67, v149, v8
	v_fmac_f32_e32 v66, v150, v9
	v_fmac_f32_e32 v67, v151, v10
	ds_read_b128 v[148:151], v105 offset:42592
	s_waitcnt lgkmcnt(11)
	v_fmac_f32_e32 v66, v152, v11
	v_fmac_f32_e32 v67, v153, v12
	v_fmac_f32_e32 v66, v154, v13
	v_fmac_f32_e32 v67, v155, v14
	ds_read_b128 v[152:155], v105 offset:42752
	s_waitcnt lgkmcnt(11)
	v_fmac_f32_e32 v66, v156, v15
	v_fmac_f32_e32 v67, v157, v16
	v_fmac_f32_e32 v66, v158, v17
	v_fmac_f32_e32 v67, v159, v18
	ds_read_b128 v[156:159], v105 offset:42768
	s_waitcnt lgkmcnt(11)
	v_fmac_f32_e32 v66, v160, v20
	v_fmac_f32_e32 v67, v161, v21
	v_fmac_f32_e32 v66, v162, v22
	v_fmac_f32_e32 v67, v163, v23
	ds_read_b128 v[160:163], v105 offset:42784
	s_waitcnt lgkmcnt(11)
	v_fmac_f32_e32 v66, v164, v24
	v_fmac_f32_e32 v67, v165, v25
	v_fmac_f32_e32 v66, v166, v26
	v_fmac_f32_e32 v67, v167, v27
	ds_read_b128 v[164:167], v105 offset:42800
	s_waitcnt lgkmcnt(11)
	v_fmac_f32_e32 v66, v168, v28
	v_fmac_f32_e32 v67, v169, v29
	v_fmac_f32_e32 v66, v170, v30
	v_sub_f32_e32 v31, v31, v66
	v_sub_f32_e32 v31, v31, v67
	ds_read_b128 v[168:171], v105 offset:42816
	s_waitcnt lgkmcnt(11)
	v_mul_f32_e32 v66, v172, v0
	v_mul_f32_e32 v67, v173, v4
	v_fmac_f32_e32 v66, v174, v5
	v_fmac_f32_e32 v67, v175, v6
	ds_read_b128 v[172:175], v105 offset:42832
	s_waitcnt lgkmcnt(11)
	v_fmac_f32_e32 v66, v176, v7
	v_fmac_f32_e32 v67, v177, v8
	v_fmac_f32_e32 v66, v178, v9
	v_fmac_f32_e32 v67, v179, v10
	ds_read_b128 v[176:179], v105 offset:42848
	s_waitcnt lgkmcnt(11)
	v_fmac_f32_e32 v66, v180, v11
	v_fmac_f32_e32 v67, v181, v12
	v_fmac_f32_e32 v66, v182, v13
	v_fmac_f32_e32 v67, v183, v14
	ds_read_b128 v[180:183], v105 offset:42864
	s_waitcnt lgkmcnt(11)
	v_fmac_f32_e32 v66, v136, v15
	v_fmac_f32_e32 v67, v137, v16
	v_fmac_f32_e32 v66, v138, v17
	v_fmac_f32_e32 v67, v139, v18
	ds_read_b128 v[136:139], v105 offset:43008
	s_waitcnt lgkmcnt(11)
	v_fmac_f32_e32 v66, v140, v20
	v_fmac_f32_e32 v67, v141, v21
	v_fmac_f32_e32 v66, v142, v22
	v_fmac_f32_e32 v67, v143, v23
	ds_read_b128 v[140:143], v105 offset:43024
	s_waitcnt lgkmcnt(11)
	v_fmac_f32_e32 v66, v144, v24
	v_fmac_f32_e32 v67, v145, v25
	v_fmac_f32_e32 v66, v146, v26
	v_fmac_f32_e32 v67, v147, v27
	ds_read_b128 v[144:147], v105 offset:43040
	s_waitcnt lgkmcnt(11)
	v_fmac_f32_e32 v66, v148, v28
	v_fmac_f32_e32 v67, v149, v29
	v_fmac_f32_e32 v66, v150, v30
	v_fmac_f32_e32 v67, v151, v31
	v_sub_f32_e32 v32, v32, v66
	v_sub_f32_e32 v32, v32, v67
	ds_read_b128 v[148:151], v105 offset:43056
	s_waitcnt lgkmcnt(11)
	v_mul_f32_e32 v66, v152, v0
	v_mul_f32_e32 v67, v153, v4
	v_fmac_f32_e32 v66, v154, v5
	v_fmac_f32_e32 v67, v155, v6
	ds_read_b128 v[152:155], v105 offset:43072
	s_waitcnt lgkmcnt(11)
	v_fmac_f32_e32 v66, v156, v7
	v_fmac_f32_e32 v67, v157, v8
	v_fmac_f32_e32 v66, v158, v9
	v_fmac_f32_e32 v67, v159, v10
	ds_read_b128 v[156:159], v105 offset:43088
	s_waitcnt lgkmcnt(11)
	v_fmac_f32_e32 v66, v160, v11
	v_fmac_f32_e32 v67, v161, v12
	v_fmac_f32_e32 v66, v162, v13
	v_fmac_f32_e32 v67, v163, v14
	ds_read_b128 v[160:163], v105 offset:43104
	s_waitcnt lgkmcnt(11)
	v_fmac_f32_e32 v66, v164, v15
	v_fmac_f32_e32 v67, v165, v16
	v_fmac_f32_e32 v66, v166, v17
	v_fmac_f32_e32 v67, v167, v18
	ds_read_b128 v[164:167], v105 offset:43120
	s_waitcnt lgkmcnt(11)
	v_fmac_f32_e32 v66, v168, v20
	v_fmac_f32_e32 v67, v169, v21
	v_fmac_f32_e32 v66, v170, v22
	v_fmac_f32_e32 v67, v171, v23
	ds_read_b128 v[168:171], v105 offset:43264
	s_waitcnt lgkmcnt(11)
	v_fmac_f32_e32 v66, v172, v24
	v_fmac_f32_e32 v67, v173, v25
	v_fmac_f32_e32 v66, v174, v26
	v_fmac_f32_e32 v67, v175, v27
	ds_read_b128 v[172:175], v105 offset:43280
	s_waitcnt lgkmcnt(11)
	v_fmac_f32_e32 v66, v176, v28
	v_fmac_f32_e32 v67, v177, v29
	v_fmac_f32_e32 v66, v178, v30
	v_fmac_f32_e32 v67, v179, v31
	ds_read_b128 v[176:179], v105 offset:43296
	s_waitcnt lgkmcnt(11)
	v_fmac_f32_e32 v66, v180, v32
	v_sub_f32_e32 v33, v33, v66
	v_sub_f32_e32 v33, v33, v67
	ds_read_b128 v[180:183], v105 offset:43312
	s_waitcnt lgkmcnt(11)
	v_mul_f32_e32 v66, v136, v0
	v_mul_f32_e32 v67, v137, v4
	v_fmac_f32_e32 v66, v138, v5
	v_fmac_f32_e32 v67, v139, v6
	ds_read_b128 v[136:139], v105 offset:43328
	s_waitcnt lgkmcnt(11)
	v_fmac_f32_e32 v66, v140, v7
	v_fmac_f32_e32 v67, v141, v8
	v_fmac_f32_e32 v66, v142, v9
	v_fmac_f32_e32 v67, v143, v10
	ds_read_b128 v[140:143], v105 offset:43344
	s_waitcnt lgkmcnt(11)
	v_fmac_f32_e32 v66, v144, v11
	v_fmac_f32_e32 v67, v145, v12
	v_fmac_f32_e32 v66, v146, v13
	v_fmac_f32_e32 v67, v147, v14
	ds_read_b128 v[144:147], v105 offset:43360
	s_waitcnt lgkmcnt(11)
	v_fmac_f32_e32 v66, v148, v15
	v_fmac_f32_e32 v67, v149, v16
	v_fmac_f32_e32 v66, v150, v17
	v_fmac_f32_e32 v67, v151, v18
	ds_read_b128 v[148:151], v105 offset:43376
	s_waitcnt lgkmcnt(11)
	v_fmac_f32_e32 v66, v152, v20
	v_fmac_f32_e32 v67, v153, v21
	v_fmac_f32_e32 v66, v154, v22
	v_fmac_f32_e32 v67, v155, v23
	ds_read_b128 v[152:155], v105 offset:43520
	s_waitcnt lgkmcnt(11)
	v_fmac_f32_e32 v66, v156, v24
	v_fmac_f32_e32 v67, v157, v25
	v_fmac_f32_e32 v66, v158, v26
	v_fmac_f32_e32 v67, v159, v27
	ds_read_b128 v[156:159], v105 offset:43536
	s_waitcnt lgkmcnt(11)
	v_fmac_f32_e32 v66, v160, v28
	v_fmac_f32_e32 v67, v161, v29
	v_fmac_f32_e32 v66, v162, v30
	v_fmac_f32_e32 v67, v163, v31
	ds_read_b128 v[160:163], v105 offset:43552
	s_waitcnt lgkmcnt(11)
	v_fmac_f32_e32 v66, v164, v32
	v_fmac_f32_e32 v67, v165, v33
	v_sub_f32_e32 v34, v34, v66
	v_sub_f32_e32 v34, v34, v67
	ds_read_b128 v[164:167], v105 offset:43568
	s_waitcnt lgkmcnt(11)
	v_mul_f32_e32 v66, v168, v0
	v_mul_f32_e32 v67, v169, v4
	v_fmac_f32_e32 v66, v170, v5
	v_fmac_f32_e32 v67, v171, v6
	ds_read_b128 v[168:171], v105 offset:43584
	s_waitcnt lgkmcnt(11)
	v_fmac_f32_e32 v66, v172, v7
	v_fmac_f32_e32 v67, v173, v8
	v_fmac_f32_e32 v66, v174, v9
	v_fmac_f32_e32 v67, v175, v10
	ds_read_b128 v[172:175], v105 offset:43600
	s_waitcnt lgkmcnt(11)
	v_fmac_f32_e32 v66, v176, v11
	v_fmac_f32_e32 v67, v177, v12
	v_fmac_f32_e32 v66, v178, v13
	v_fmac_f32_e32 v67, v179, v14
	ds_read_b128 v[176:179], v105 offset:43616
	s_waitcnt lgkmcnt(11)
	v_fmac_f32_e32 v66, v180, v15
	v_fmac_f32_e32 v67, v181, v16
	v_fmac_f32_e32 v66, v182, v17
	v_fmac_f32_e32 v67, v183, v18
	ds_read_b128 v[180:183], v105 offset:43632
	s_waitcnt lgkmcnt(11)
	v_fmac_f32_e32 v66, v136, v20
	v_fmac_f32_e32 v67, v137, v21
	v_fmac_f32_e32 v66, v138, v22
	v_fmac_f32_e32 v67, v139, v23
	ds_read_b128 v[136:139], v105 offset:43776
	s_waitcnt lgkmcnt(11)
	v_fmac_f32_e32 v66, v140, v24
	v_fmac_f32_e32 v67, v141, v25
	v_fmac_f32_e32 v66, v142, v26
	v_fmac_f32_e32 v67, v143, v27
	ds_read_b128 v[140:143], v105 offset:43792
	s_waitcnt lgkmcnt(11)
	v_fmac_f32_e32 v66, v144, v28
	v_fmac_f32_e32 v67, v145, v29
	v_fmac_f32_e32 v66, v146, v30
	v_fmac_f32_e32 v67, v147, v31
	ds_read_b128 v[144:147], v105 offset:43808
	s_waitcnt lgkmcnt(11)
	v_fmac_f32_e32 v66, v148, v32
	v_fmac_f32_e32 v67, v149, v33
	v_fmac_f32_e32 v66, v150, v34
	v_sub_f32_e32 v35, v35, v66
	v_sub_f32_e32 v35, v35, v67
	ds_read_b128 v[148:151], v105 offset:43824
	s_waitcnt lgkmcnt(11)
	v_mul_f32_e32 v66, v152, v0
	v_mul_f32_e32 v67, v153, v4
	v_fmac_f32_e32 v66, v154, v5
	v_fmac_f32_e32 v67, v155, v6
	ds_read_b128 v[152:155], v105 offset:43840
	s_waitcnt lgkmcnt(11)
	v_fmac_f32_e32 v66, v156, v7
	v_fmac_f32_e32 v67, v157, v8
	v_fmac_f32_e32 v66, v158, v9
	v_fmac_f32_e32 v67, v159, v10
	ds_read_b128 v[156:159], v105 offset:43856
	s_waitcnt lgkmcnt(11)
	v_fmac_f32_e32 v66, v160, v11
	v_fmac_f32_e32 v67, v161, v12
	v_fmac_f32_e32 v66, v162, v13
	v_fmac_f32_e32 v67, v163, v14
	ds_read_b128 v[160:163], v105 offset:43872
	s_waitcnt lgkmcnt(11)
	v_fmac_f32_e32 v66, v164, v15
	v_fmac_f32_e32 v67, v165, v16
	v_fmac_f32_e32 v66, v166, v17
	v_fmac_f32_e32 v67, v167, v18
	ds_read_b128 v[164:167], v105 offset:43888
	s_waitcnt lgkmcnt(11)
	v_fmac_f32_e32 v66, v168, v20
	v_fmac_f32_e32 v67, v169, v21
	v_fmac_f32_e32 v66, v170, v22
	v_fmac_f32_e32 v67, v171, v23
	ds_read_b128 v[168:171], v105 offset:43904
	s_waitcnt lgkmcnt(11)
	v_fmac_f32_e32 v66, v172, v24
	v_fmac_f32_e32 v67, v173, v25
	v_fmac_f32_e32 v66, v174, v26
	v_fmac_f32_e32 v67, v175, v27
	ds_read_b128 v[172:175], v105 offset:44032
	s_waitcnt lgkmcnt(11)
	v_fmac_f32_e32 v66, v176, v28
	v_fmac_f32_e32 v67, v177, v29
	v_fmac_f32_e32 v66, v178, v30
	v_fmac_f32_e32 v67, v179, v31
	ds_read_b128 v[176:179], v105 offset:44048
	s_waitcnt lgkmcnt(11)
	v_fmac_f32_e32 v66, v180, v32
	v_fmac_f32_e32 v67, v181, v33
	v_fmac_f32_e32 v66, v182, v34
	v_fmac_f32_e32 v67, v183, v35
	v_sub_f32_e32 v36, v36, v66
	v_sub_f32_e32 v36, v36, v67
	ds_read_b128 v[180:183], v105 offset:44064
	s_waitcnt lgkmcnt(11)
	v_mul_f32_e32 v66, v136, v0
	v_mul_f32_e32 v67, v137, v4
	v_fmac_f32_e32 v66, v138, v5
	v_fmac_f32_e32 v67, v139, v6
	ds_read_b128 v[136:139], v105 offset:44080
	s_waitcnt lgkmcnt(11)
	v_fmac_f32_e32 v66, v140, v7
	v_fmac_f32_e32 v67, v141, v8
	v_fmac_f32_e32 v66, v142, v9
	v_fmac_f32_e32 v67, v143, v10
	ds_read_b128 v[140:143], v105 offset:44096
	s_waitcnt lgkmcnt(11)
	v_fmac_f32_e32 v66, v144, v11
	v_fmac_f32_e32 v67, v145, v12
	v_fmac_f32_e32 v66, v146, v13
	v_fmac_f32_e32 v67, v147, v14
	ds_read_b128 v[144:147], v105 offset:44112
	s_waitcnt lgkmcnt(11)
	v_fmac_f32_e32 v66, v148, v15
	v_fmac_f32_e32 v67, v149, v16
	v_fmac_f32_e32 v66, v150, v17
	v_fmac_f32_e32 v67, v151, v18
	ds_read_b128 v[148:151], v105 offset:44128
	s_waitcnt lgkmcnt(11)
	v_fmac_f32_e32 v66, v152, v20
	v_fmac_f32_e32 v67, v153, v21
	v_fmac_f32_e32 v66, v154, v22
	v_fmac_f32_e32 v67, v155, v23
	ds_read_b128 v[152:155], v105 offset:44144
	s_waitcnt lgkmcnt(11)
	v_fmac_f32_e32 v66, v156, v24
	v_fmac_f32_e32 v67, v157, v25
	v_fmac_f32_e32 v66, v158, v26
	v_fmac_f32_e32 v67, v159, v27
	ds_read_b128 v[156:159], v105 offset:44160
	s_waitcnt lgkmcnt(11)
	v_fmac_f32_e32 v66, v160, v28
	v_fmac_f32_e32 v67, v161, v29
	v_fmac_f32_e32 v66, v162, v30
	v_fmac_f32_e32 v67, v163, v31
	ds_read_b128 v[160:163], v105 offset:44288
	s_waitcnt lgkmcnt(11)
	v_fmac_f32_e32 v66, v164, v32
	v_fmac_f32_e32 v67, v165, v33
	v_fmac_f32_e32 v66, v166, v34
	v_fmac_f32_e32 v67, v167, v35
	ds_read_b128 v[164:167], v105 offset:44304
	s_waitcnt lgkmcnt(11)
	v_fmac_f32_e32 v66, v168, v36
	v_sub_f32_e32 v37, v37, v66
	v_sub_f32_e32 v37, v37, v67
	ds_read_b128 v[168:171], v105 offset:44320
	s_waitcnt lgkmcnt(11)
	v_mul_f32_e32 v66, v172, v0
	v_mul_f32_e32 v67, v173, v4
	v_fmac_f32_e32 v66, v174, v5
	v_fmac_f32_e32 v67, v175, v6
	ds_read_b128 v[172:175], v105 offset:44336
	s_waitcnt lgkmcnt(11)
	v_fmac_f32_e32 v66, v176, v7
	v_fmac_f32_e32 v67, v177, v8
	v_fmac_f32_e32 v66, v178, v9
	v_fmac_f32_e32 v67, v179, v10
	ds_read_b128 v[176:179], v105 offset:44352
	s_waitcnt lgkmcnt(11)
	v_fmac_f32_e32 v66, v180, v11
	v_fmac_f32_e32 v67, v181, v12
	v_fmac_f32_e32 v66, v182, v13
	v_fmac_f32_e32 v67, v183, v14
	ds_read_b128 v[180:183], v105 offset:44368
	s_waitcnt lgkmcnt(11)
	v_fmac_f32_e32 v66, v136, v15
	v_fmac_f32_e32 v67, v137, v16
	v_fmac_f32_e32 v66, v138, v17
	v_fmac_f32_e32 v67, v139, v18
	ds_read_b128 v[136:139], v105 offset:44384
	s_waitcnt lgkmcnt(11)
	v_fmac_f32_e32 v66, v140, v20
	v_fmac_f32_e32 v67, v141, v21
	v_fmac_f32_e32 v66, v142, v22
	v_fmac_f32_e32 v67, v143, v23
	ds_read_b128 v[140:143], v105 offset:44400
	s_waitcnt lgkmcnt(11)
	v_fmac_f32_e32 v66, v144, v24
	v_fmac_f32_e32 v67, v145, v25
	v_fmac_f32_e32 v66, v146, v26
	v_fmac_f32_e32 v67, v147, v27
	ds_read_b128 v[144:147], v105 offset:44416
	s_waitcnt lgkmcnt(11)
	v_fmac_f32_e32 v66, v148, v28
	v_fmac_f32_e32 v67, v149, v29
	v_fmac_f32_e32 v66, v150, v30
	v_fmac_f32_e32 v67, v151, v31
	ds_read_b128 v[148:151], v105 offset:44544
	s_waitcnt lgkmcnt(11)
	v_fmac_f32_e32 v66, v152, v32
	v_fmac_f32_e32 v67, v153, v33
	v_fmac_f32_e32 v66, v154, v34
	v_fmac_f32_e32 v67, v155, v35
	ds_read_b128 v[152:155], v105 offset:44560
	s_waitcnt lgkmcnt(11)
	v_fmac_f32_e32 v66, v156, v36
	v_fmac_f32_e32 v67, v157, v37
	v_sub_f32_e32 v38, v38, v66
	v_sub_f32_e32 v38, v38, v67
	ds_read_b128 v[156:159], v105 offset:44576
	s_waitcnt lgkmcnt(11)
	v_mul_f32_e32 v66, v160, v0
	v_mul_f32_e32 v67, v161, v4
	v_fmac_f32_e32 v66, v162, v5
	v_fmac_f32_e32 v67, v163, v6
	ds_read_b128 v[160:163], v105 offset:44592
	s_waitcnt lgkmcnt(11)
	v_fmac_f32_e32 v66, v164, v7
	v_fmac_f32_e32 v67, v165, v8
	v_fmac_f32_e32 v66, v166, v9
	v_fmac_f32_e32 v67, v167, v10
	ds_read_b128 v[164:167], v105 offset:44608
	s_waitcnt lgkmcnt(11)
	v_fmac_f32_e32 v66, v168, v11
	v_fmac_f32_e32 v67, v169, v12
	v_fmac_f32_e32 v66, v170, v13
	v_fmac_f32_e32 v67, v171, v14
	ds_read_b128 v[168:171], v105 offset:44624
	s_waitcnt lgkmcnt(11)
	v_fmac_f32_e32 v66, v172, v15
	v_fmac_f32_e32 v67, v173, v16
	v_fmac_f32_e32 v66, v174, v17
	v_fmac_f32_e32 v67, v175, v18
	ds_read_b128 v[172:175], v105 offset:44640
	s_waitcnt lgkmcnt(11)
	v_fmac_f32_e32 v66, v176, v20
	v_fmac_f32_e32 v67, v177, v21
	v_fmac_f32_e32 v66, v178, v22
	v_fmac_f32_e32 v67, v179, v23
	ds_read_b128 v[176:179], v105 offset:44656
	s_waitcnt lgkmcnt(11)
	v_fmac_f32_e32 v66, v180, v24
	v_fmac_f32_e32 v67, v181, v25
	v_fmac_f32_e32 v66, v182, v26
	v_fmac_f32_e32 v67, v183, v27
	ds_read_b128 v[180:183], v105 offset:44672
	s_waitcnt lgkmcnt(11)
	v_fmac_f32_e32 v66, v136, v28
	v_fmac_f32_e32 v67, v137, v29
	v_fmac_f32_e32 v66, v138, v30
	v_fmac_f32_e32 v67, v139, v31
	ds_read_b128 v[136:139], v105 offset:44800
	s_waitcnt lgkmcnt(11)
	v_fmac_f32_e32 v66, v140, v32
	v_fmac_f32_e32 v67, v141, v33
	v_fmac_f32_e32 v66, v142, v34
	v_fmac_f32_e32 v67, v143, v35
	ds_read_b128 v[140:143], v105 offset:44816
	s_waitcnt lgkmcnt(11)
	v_fmac_f32_e32 v66, v144, v36
	v_fmac_f32_e32 v67, v145, v37
	v_fmac_f32_e32 v66, v146, v38
	v_sub_f32_e32 v39, v39, v66
	v_sub_f32_e32 v39, v39, v67
	ds_read_b128 v[144:147], v105 offset:44832
	s_waitcnt lgkmcnt(11)
	v_mul_f32_e32 v66, v148, v0
	v_mul_f32_e32 v67, v149, v4
	v_fmac_f32_e32 v66, v150, v5
	v_fmac_f32_e32 v67, v151, v6
	ds_read_b128 v[148:151], v105 offset:44848
	s_waitcnt lgkmcnt(11)
	v_fmac_f32_e32 v66, v152, v7
	v_fmac_f32_e32 v67, v153, v8
	v_fmac_f32_e32 v66, v154, v9
	v_fmac_f32_e32 v67, v155, v10
	ds_read_b128 v[152:155], v105 offset:44864
	s_waitcnt lgkmcnt(11)
	v_fmac_f32_e32 v66, v156, v11
	v_fmac_f32_e32 v67, v157, v12
	v_fmac_f32_e32 v66, v158, v13
	v_fmac_f32_e32 v67, v159, v14
	ds_read_b128 v[156:159], v105 offset:44880
	s_waitcnt lgkmcnt(11)
	v_fmac_f32_e32 v66, v160, v15
	v_fmac_f32_e32 v67, v161, v16
	v_fmac_f32_e32 v66, v162, v17
	v_fmac_f32_e32 v67, v163, v18
	ds_read_b128 v[160:163], v105 offset:44896
	s_waitcnt lgkmcnt(11)
	v_fmac_f32_e32 v66, v164, v20
	v_fmac_f32_e32 v67, v165, v21
	v_fmac_f32_e32 v66, v166, v22
	v_fmac_f32_e32 v67, v167, v23
	ds_read_b128 v[164:167], v105 offset:44912
	s_waitcnt lgkmcnt(11)
	v_fmac_f32_e32 v66, v168, v24
	v_fmac_f32_e32 v67, v169, v25
	v_fmac_f32_e32 v66, v170, v26
	v_fmac_f32_e32 v67, v171, v27
	ds_read_b128 v[168:171], v105 offset:44928
	s_waitcnt lgkmcnt(11)
	v_fmac_f32_e32 v66, v172, v28
	v_fmac_f32_e32 v67, v173, v29
	v_fmac_f32_e32 v66, v174, v30
	v_fmac_f32_e32 v67, v175, v31
	ds_read_b128 v[172:175], v105 offset:44944
	s_waitcnt lgkmcnt(11)
	v_fmac_f32_e32 v66, v176, v32
	v_fmac_f32_e32 v67, v177, v33
	v_fmac_f32_e32 v66, v178, v34
	v_fmac_f32_e32 v67, v179, v35
	ds_read_b128 v[176:179], v105 offset:45056
	s_waitcnt lgkmcnt(11)
	v_fmac_f32_e32 v66, v180, v36
	v_fmac_f32_e32 v67, v181, v37
	v_fmac_f32_e32 v66, v182, v38
	v_fmac_f32_e32 v67, v183, v39
	v_sub_f32_e32 v40, v40, v66
	v_sub_f32_e32 v40, v40, v67
	ds_read_b128 v[180:183], v105 offset:45072
	s_waitcnt lgkmcnt(11)
	v_mul_f32_e32 v66, v136, v0
	v_mul_f32_e32 v67, v137, v4
	v_fmac_f32_e32 v66, v138, v5
	v_fmac_f32_e32 v67, v139, v6
	ds_read_b128 v[136:139], v105 offset:45088
	s_waitcnt lgkmcnt(11)
	v_fmac_f32_e32 v66, v140, v7
	v_fmac_f32_e32 v67, v141, v8
	v_fmac_f32_e32 v66, v142, v9
	v_fmac_f32_e32 v67, v143, v10
	ds_read_b128 v[140:143], v105 offset:45104
	s_waitcnt lgkmcnt(11)
	v_fmac_f32_e32 v66, v144, v11
	v_fmac_f32_e32 v67, v145, v12
	v_fmac_f32_e32 v66, v146, v13
	v_fmac_f32_e32 v67, v147, v14
	ds_read_b128 v[144:147], v105 offset:45120
	s_waitcnt lgkmcnt(11)
	v_fmac_f32_e32 v66, v148, v15
	v_fmac_f32_e32 v67, v149, v16
	v_fmac_f32_e32 v66, v150, v17
	v_fmac_f32_e32 v67, v151, v18
	ds_read_b128 v[148:151], v105 offset:45136
	s_waitcnt lgkmcnt(11)
	v_fmac_f32_e32 v66, v152, v20
	v_fmac_f32_e32 v67, v153, v21
	v_fmac_f32_e32 v66, v154, v22
	v_fmac_f32_e32 v67, v155, v23
	ds_read_b128 v[152:155], v105 offset:45152
	s_waitcnt lgkmcnt(11)
	v_fmac_f32_e32 v66, v156, v24
	v_fmac_f32_e32 v67, v157, v25
	v_fmac_f32_e32 v66, v158, v26
	v_fmac_f32_e32 v67, v159, v27
	ds_read_b128 v[156:159], v105 offset:45168
	s_waitcnt lgkmcnt(11)
	v_fmac_f32_e32 v66, v160, v28
	v_fmac_f32_e32 v67, v161, v29
	v_fmac_f32_e32 v66, v162, v30
	v_fmac_f32_e32 v67, v163, v31
	ds_read_b128 v[160:163], v105 offset:45184
	s_waitcnt lgkmcnt(11)
	v_fmac_f32_e32 v66, v164, v32
	v_fmac_f32_e32 v67, v165, v33
	v_fmac_f32_e32 v66, v166, v34
	v_fmac_f32_e32 v67, v167, v35
	ds_read_b128 v[164:167], v105 offset:45200
	s_waitcnt lgkmcnt(11)
	v_fmac_f32_e32 v66, v168, v36
	v_fmac_f32_e32 v67, v169, v37
	v_fmac_f32_e32 v66, v170, v38
	v_fmac_f32_e32 v67, v171, v39
	ds_read_b128 v[168:171], v105 offset:45312
	s_waitcnt lgkmcnt(11)
	v_fmac_f32_e32 v66, v172, v40
	v_sub_f32_e32 v41, v41, v66
	v_sub_f32_e32 v41, v41, v67
	ds_read_b128 v[172:175], v105 offset:45328
	s_waitcnt lgkmcnt(11)
	v_mul_f32_e32 v66, v176, v0
	v_mul_f32_e32 v67, v177, v4
	v_fmac_f32_e32 v66, v178, v5
	v_fmac_f32_e32 v67, v179, v6
	ds_read_b128 v[176:179], v105 offset:45344
	s_waitcnt lgkmcnt(11)
	v_fmac_f32_e32 v66, v180, v7
	v_fmac_f32_e32 v67, v181, v8
	v_fmac_f32_e32 v66, v182, v9
	v_fmac_f32_e32 v67, v183, v10
	ds_read_b128 v[180:183], v105 offset:45360
	s_waitcnt lgkmcnt(11)
	v_fmac_f32_e32 v66, v136, v11
	v_fmac_f32_e32 v67, v137, v12
	v_fmac_f32_e32 v66, v138, v13
	v_fmac_f32_e32 v67, v139, v14
	ds_read_b128 v[136:139], v105 offset:45376
	s_waitcnt lgkmcnt(11)
	v_fmac_f32_e32 v66, v140, v15
	v_fmac_f32_e32 v67, v141, v16
	v_fmac_f32_e32 v66, v142, v17
	v_fmac_f32_e32 v67, v143, v18
	ds_read_b128 v[140:143], v105 offset:45392
	s_waitcnt lgkmcnt(11)
	v_fmac_f32_e32 v66, v144, v20
	v_fmac_f32_e32 v67, v145, v21
	v_fmac_f32_e32 v66, v146, v22
	v_fmac_f32_e32 v67, v147, v23
	ds_read_b128 v[144:147], v105 offset:45408
	s_waitcnt lgkmcnt(11)
	v_fmac_f32_e32 v66, v148, v24
	v_fmac_f32_e32 v67, v149, v25
	v_fmac_f32_e32 v66, v150, v26
	v_fmac_f32_e32 v67, v151, v27
	ds_read_b128 v[148:151], v105 offset:45424
	s_waitcnt lgkmcnt(11)
	v_fmac_f32_e32 v66, v152, v28
	v_fmac_f32_e32 v67, v153, v29
	v_fmac_f32_e32 v66, v154, v30
	v_fmac_f32_e32 v67, v155, v31
	ds_read_b128 v[152:155], v105 offset:45440
	s_waitcnt lgkmcnt(11)
	v_fmac_f32_e32 v66, v156, v32
	v_fmac_f32_e32 v67, v157, v33
	v_fmac_f32_e32 v66, v158, v34
	v_fmac_f32_e32 v67, v159, v35
	ds_read_b128 v[156:159], v105 offset:45456
	s_waitcnt lgkmcnt(11)
	v_fmac_f32_e32 v66, v160, v36
	v_fmac_f32_e32 v67, v161, v37
	v_fmac_f32_e32 v66, v162, v38
	v_fmac_f32_e32 v67, v163, v39
	ds_read_b128 v[160:163], v105 offset:45568
	s_waitcnt lgkmcnt(11)
	v_fmac_f32_e32 v66, v164, v40
	v_fmac_f32_e32 v67, v165, v41
	v_sub_f32_e32 v42, v42, v66
	v_sub_f32_e32 v42, v42, v67
	ds_read_b128 v[164:167], v105 offset:45584
	s_waitcnt lgkmcnt(11)
	v_mul_f32_e32 v66, v168, v0
	v_mul_f32_e32 v67, v169, v4
	v_fmac_f32_e32 v66, v170, v5
	v_fmac_f32_e32 v67, v171, v6
	ds_read_b128 v[168:171], v105 offset:45600
	s_waitcnt lgkmcnt(11)
	v_fmac_f32_e32 v66, v172, v7
	v_fmac_f32_e32 v67, v173, v8
	v_fmac_f32_e32 v66, v174, v9
	v_fmac_f32_e32 v67, v175, v10
	ds_read_b128 v[172:175], v105 offset:45616
	s_waitcnt lgkmcnt(11)
	v_fmac_f32_e32 v66, v176, v11
	v_fmac_f32_e32 v67, v177, v12
	v_fmac_f32_e32 v66, v178, v13
	v_fmac_f32_e32 v67, v179, v14
	ds_read_b128 v[176:179], v105 offset:45632
	s_waitcnt lgkmcnt(11)
	v_fmac_f32_e32 v66, v180, v15
	v_fmac_f32_e32 v67, v181, v16
	v_fmac_f32_e32 v66, v182, v17
	v_fmac_f32_e32 v67, v183, v18
	ds_read_b128 v[180:183], v105 offset:45648
	s_waitcnt lgkmcnt(11)
	v_fmac_f32_e32 v66, v136, v20
	v_fmac_f32_e32 v67, v137, v21
	v_fmac_f32_e32 v66, v138, v22
	v_fmac_f32_e32 v67, v139, v23
	ds_read_b128 v[136:139], v105 offset:45664
	s_waitcnt lgkmcnt(11)
	v_fmac_f32_e32 v66, v140, v24
	v_fmac_f32_e32 v67, v141, v25
	v_fmac_f32_e32 v66, v142, v26
	v_fmac_f32_e32 v67, v143, v27
	ds_read_b128 v[140:143], v105 offset:45680
	s_waitcnt lgkmcnt(11)
	v_fmac_f32_e32 v66, v144, v28
	v_fmac_f32_e32 v67, v145, v29
	v_fmac_f32_e32 v66, v146, v30
	v_fmac_f32_e32 v67, v147, v31
	ds_read_b128 v[144:147], v105 offset:45696
	s_waitcnt lgkmcnt(11)
	v_fmac_f32_e32 v66, v148, v32
	v_fmac_f32_e32 v67, v149, v33
	v_fmac_f32_e32 v66, v150, v34
	v_fmac_f32_e32 v67, v151, v35
	ds_read_b128 v[148:151], v105 offset:45712
	s_waitcnt lgkmcnt(11)
	v_fmac_f32_e32 v66, v152, v36
	v_fmac_f32_e32 v67, v153, v37
	v_fmac_f32_e32 v66, v154, v38
	v_fmac_f32_e32 v67, v155, v39
	ds_read_b128 v[152:155], v105 offset:45824
	s_waitcnt lgkmcnt(11)
	v_fmac_f32_e32 v66, v156, v40
	v_fmac_f32_e32 v67, v157, v41
	v_fmac_f32_e32 v66, v158, v42
	v_sub_f32_e32 v43, v43, v66
	v_sub_f32_e32 v43, v43, v67
	ds_read_b128 v[156:159], v105 offset:45840
	s_waitcnt lgkmcnt(11)
	v_mul_f32_e32 v66, v160, v0
	v_mul_f32_e32 v67, v161, v4
	v_fmac_f32_e32 v66, v162, v5
	v_fmac_f32_e32 v67, v163, v6
	ds_read_b128 v[160:163], v105 offset:45856
	s_waitcnt lgkmcnt(11)
	v_fmac_f32_e32 v66, v164, v7
	v_fmac_f32_e32 v67, v165, v8
	v_fmac_f32_e32 v66, v166, v9
	v_fmac_f32_e32 v67, v167, v10
	ds_read_b128 v[164:167], v105 offset:45872
	s_waitcnt lgkmcnt(11)
	v_fmac_f32_e32 v66, v168, v11
	v_fmac_f32_e32 v67, v169, v12
	v_fmac_f32_e32 v66, v170, v13
	v_fmac_f32_e32 v67, v171, v14
	ds_read_b128 v[168:171], v105 offset:45888
	s_waitcnt lgkmcnt(11)
	v_fmac_f32_e32 v66, v172, v15
	v_fmac_f32_e32 v67, v173, v16
	v_fmac_f32_e32 v66, v174, v17
	v_fmac_f32_e32 v67, v175, v18
	ds_read_b128 v[172:175], v105 offset:45904
	s_waitcnt lgkmcnt(11)
	v_fmac_f32_e32 v66, v176, v20
	v_fmac_f32_e32 v67, v177, v21
	v_fmac_f32_e32 v66, v178, v22
	v_fmac_f32_e32 v67, v179, v23
	ds_read_b128 v[176:179], v105 offset:45920
	s_waitcnt lgkmcnt(11)
	v_fmac_f32_e32 v66, v180, v24
	v_fmac_f32_e32 v67, v181, v25
	v_fmac_f32_e32 v66, v182, v26
	v_fmac_f32_e32 v67, v183, v27
	ds_read_b128 v[180:183], v105 offset:45936
	s_waitcnt lgkmcnt(11)
	v_fmac_f32_e32 v66, v136, v28
	v_fmac_f32_e32 v67, v137, v29
	v_fmac_f32_e32 v66, v138, v30
	v_fmac_f32_e32 v67, v139, v31
	ds_read_b128 v[136:139], v105 offset:45952
	s_waitcnt lgkmcnt(11)
	v_fmac_f32_e32 v66, v140, v32
	v_fmac_f32_e32 v67, v141, v33
	v_fmac_f32_e32 v66, v142, v34
	v_fmac_f32_e32 v67, v143, v35
	ds_read_b128 v[140:143], v105 offset:45968
	s_waitcnt lgkmcnt(11)
	v_fmac_f32_e32 v66, v144, v36
	v_fmac_f32_e32 v67, v145, v37
	v_fmac_f32_e32 v66, v146, v38
	v_fmac_f32_e32 v67, v147, v39
	ds_read_b128 v[144:147], v105 offset:45984
	s_waitcnt lgkmcnt(11)
	v_fmac_f32_e32 v66, v148, v40
	v_fmac_f32_e32 v67, v149, v41
	v_fmac_f32_e32 v66, v150, v42
	v_fmac_f32_e32 v67, v151, v43
	v_sub_f32_e32 v44, v44, v66
	v_sub_f32_e32 v44, v44, v67
	ds_read_b128 v[148:151], v105 offset:46080
	s_waitcnt lgkmcnt(11)
	v_mul_f32_e32 v66, v152, v0
	v_mul_f32_e32 v67, v153, v4
	v_fmac_f32_e32 v66, v154, v5
	v_fmac_f32_e32 v67, v155, v6
	ds_read_b128 v[152:155], v105 offset:46096
	s_waitcnt lgkmcnt(11)
	v_fmac_f32_e32 v66, v156, v7
	v_fmac_f32_e32 v67, v157, v8
	v_fmac_f32_e32 v66, v158, v9
	v_fmac_f32_e32 v67, v159, v10
	ds_read_b128 v[156:159], v105 offset:46112
	s_waitcnt lgkmcnt(11)
	v_fmac_f32_e32 v66, v160, v11
	v_fmac_f32_e32 v67, v161, v12
	v_fmac_f32_e32 v66, v162, v13
	v_fmac_f32_e32 v67, v163, v14
	ds_read_b128 v[160:163], v105 offset:46128
	s_waitcnt lgkmcnt(11)
	v_fmac_f32_e32 v66, v164, v15
	v_fmac_f32_e32 v67, v165, v16
	v_fmac_f32_e32 v66, v166, v17
	v_fmac_f32_e32 v67, v167, v18
	ds_read_b128 v[164:167], v105 offset:46144
	s_waitcnt lgkmcnt(11)
	v_fmac_f32_e32 v66, v168, v20
	v_fmac_f32_e32 v67, v169, v21
	v_fmac_f32_e32 v66, v170, v22
	v_fmac_f32_e32 v67, v171, v23
	ds_read_b128 v[168:171], v105 offset:46160
	s_waitcnt lgkmcnt(11)
	v_fmac_f32_e32 v66, v172, v24
	v_fmac_f32_e32 v67, v173, v25
	v_fmac_f32_e32 v66, v174, v26
	v_fmac_f32_e32 v67, v175, v27
	ds_read_b128 v[172:175], v105 offset:46176
	s_waitcnt lgkmcnt(11)
	v_fmac_f32_e32 v66, v176, v28
	v_fmac_f32_e32 v67, v177, v29
	v_fmac_f32_e32 v66, v178, v30
	v_fmac_f32_e32 v67, v179, v31
	ds_read_b128 v[176:179], v105 offset:46192
	s_waitcnt lgkmcnt(11)
	v_fmac_f32_e32 v66, v180, v32
	v_fmac_f32_e32 v67, v181, v33
	v_fmac_f32_e32 v66, v182, v34
	v_fmac_f32_e32 v67, v183, v35
	ds_read_b128 v[180:183], v105 offset:46208
	s_waitcnt lgkmcnt(11)
	v_fmac_f32_e32 v66, v136, v36
	v_fmac_f32_e32 v67, v137, v37
	v_fmac_f32_e32 v66, v138, v38
	v_fmac_f32_e32 v67, v139, v39
	ds_read_b128 v[136:139], v105 offset:46224
	s_waitcnt lgkmcnt(11)
	v_fmac_f32_e32 v66, v140, v40
	v_fmac_f32_e32 v67, v141, v41
	v_fmac_f32_e32 v66, v142, v42
	v_fmac_f32_e32 v67, v143, v43
	ds_read_b128 v[140:143], v105 offset:46240
	s_waitcnt lgkmcnt(11)
	v_fmac_f32_e32 v66, v144, v44
	v_sub_f32_e32 v45, v45, v66
	v_sub_f32_e32 v45, v45, v67
	ds_read_b128 v[144:147], v105 offset:46336
	s_waitcnt lgkmcnt(11)
	v_mul_f32_e32 v66, v148, v0
	v_mul_f32_e32 v67, v149, v4
	v_fmac_f32_e32 v66, v150, v5
	v_fmac_f32_e32 v67, v151, v6
	ds_read_b128 v[148:151], v105 offset:46352
	s_waitcnt lgkmcnt(11)
	v_fmac_f32_e32 v66, v152, v7
	v_fmac_f32_e32 v67, v153, v8
	v_fmac_f32_e32 v66, v154, v9
	v_fmac_f32_e32 v67, v155, v10
	ds_read_b128 v[152:155], v105 offset:46368
	s_waitcnt lgkmcnt(11)
	v_fmac_f32_e32 v66, v156, v11
	v_fmac_f32_e32 v67, v157, v12
	v_fmac_f32_e32 v66, v158, v13
	v_fmac_f32_e32 v67, v159, v14
	ds_read_b128 v[156:159], v105 offset:46384
	s_waitcnt lgkmcnt(11)
	v_fmac_f32_e32 v66, v160, v15
	v_fmac_f32_e32 v67, v161, v16
	v_fmac_f32_e32 v66, v162, v17
	v_fmac_f32_e32 v67, v163, v18
	ds_read_b128 v[160:163], v105 offset:46400
	s_waitcnt lgkmcnt(11)
	v_fmac_f32_e32 v66, v164, v20
	v_fmac_f32_e32 v67, v165, v21
	v_fmac_f32_e32 v66, v166, v22
	v_fmac_f32_e32 v67, v167, v23
	ds_read_b128 v[164:167], v105 offset:46416
	s_waitcnt lgkmcnt(11)
	v_fmac_f32_e32 v66, v168, v24
	v_fmac_f32_e32 v67, v169, v25
	v_fmac_f32_e32 v66, v170, v26
	v_fmac_f32_e32 v67, v171, v27
	ds_read_b128 v[168:171], v105 offset:46432
	s_waitcnt lgkmcnt(11)
	v_fmac_f32_e32 v66, v172, v28
	v_fmac_f32_e32 v67, v173, v29
	v_fmac_f32_e32 v66, v174, v30
	v_fmac_f32_e32 v67, v175, v31
	ds_read_b128 v[172:175], v105 offset:46448
	s_waitcnt lgkmcnt(11)
	v_fmac_f32_e32 v66, v176, v32
	v_fmac_f32_e32 v67, v177, v33
	v_fmac_f32_e32 v66, v178, v34
	v_fmac_f32_e32 v67, v179, v35
	ds_read_b128 v[176:179], v105 offset:46464
	s_waitcnt lgkmcnt(11)
	v_fmac_f32_e32 v66, v180, v36
	v_fmac_f32_e32 v67, v181, v37
	v_fmac_f32_e32 v66, v182, v38
	v_fmac_f32_e32 v67, v183, v39
	ds_read_b128 v[180:183], v105 offset:46480
	s_waitcnt lgkmcnt(11)
	v_fmac_f32_e32 v66, v136, v40
	v_fmac_f32_e32 v67, v137, v41
	v_fmac_f32_e32 v66, v138, v42
	v_fmac_f32_e32 v67, v139, v43
	ds_read_b128 v[136:139], v105 offset:46496
	s_waitcnt lgkmcnt(11)
	v_fmac_f32_e32 v66, v140, v44
	v_fmac_f32_e32 v67, v141, v45
	v_sub_f32_e32 v46, v46, v66
	v_sub_f32_e32 v46, v46, v67
	ds_read_b128 v[140:143], v105 offset:46592
	s_waitcnt lgkmcnt(11)
	v_mul_f32_e32 v66, v144, v0
	v_mul_f32_e32 v67, v145, v4
	v_fmac_f32_e32 v66, v146, v5
	v_fmac_f32_e32 v67, v147, v6
	ds_read_b128 v[144:147], v105 offset:46608
	s_waitcnt lgkmcnt(11)
	v_fmac_f32_e32 v66, v148, v7
	v_fmac_f32_e32 v67, v149, v8
	v_fmac_f32_e32 v66, v150, v9
	v_fmac_f32_e32 v67, v151, v10
	ds_read_b128 v[148:151], v105 offset:46624
	s_waitcnt lgkmcnt(11)
	v_fmac_f32_e32 v66, v152, v11
	v_fmac_f32_e32 v67, v153, v12
	v_fmac_f32_e32 v66, v154, v13
	v_fmac_f32_e32 v67, v155, v14
	ds_read_b128 v[152:155], v105 offset:46640
	s_waitcnt lgkmcnt(11)
	v_fmac_f32_e32 v66, v156, v15
	v_fmac_f32_e32 v67, v157, v16
	v_fmac_f32_e32 v66, v158, v17
	v_fmac_f32_e32 v67, v159, v18
	ds_read_b128 v[156:159], v105 offset:46656
	s_waitcnt lgkmcnt(11)
	v_fmac_f32_e32 v66, v160, v20
	v_fmac_f32_e32 v67, v161, v21
	v_fmac_f32_e32 v66, v162, v22
	v_fmac_f32_e32 v67, v163, v23
	ds_read_b128 v[160:163], v105 offset:46672
	s_waitcnt lgkmcnt(11)
	v_fmac_f32_e32 v66, v164, v24
	v_fmac_f32_e32 v67, v165, v25
	v_fmac_f32_e32 v66, v166, v26
	v_fmac_f32_e32 v67, v167, v27
	ds_read_b128 v[164:167], v105 offset:46688
	s_waitcnt lgkmcnt(11)
	v_fmac_f32_e32 v66, v168, v28
	v_fmac_f32_e32 v67, v169, v29
	v_fmac_f32_e32 v66, v170, v30
	v_fmac_f32_e32 v67, v171, v31
	ds_read_b128 v[168:171], v105 offset:46704
	s_waitcnt lgkmcnt(11)
	v_fmac_f32_e32 v66, v172, v32
	v_fmac_f32_e32 v67, v173, v33
	v_fmac_f32_e32 v66, v174, v34
	v_fmac_f32_e32 v67, v175, v35
	ds_read_b128 v[172:175], v105 offset:46720
	s_waitcnt lgkmcnt(11)
	v_fmac_f32_e32 v66, v176, v36
	v_fmac_f32_e32 v67, v177, v37
	v_fmac_f32_e32 v66, v178, v38
	v_fmac_f32_e32 v67, v179, v39
	ds_read_b128 v[176:179], v105 offset:46736
	s_waitcnt lgkmcnt(11)
	v_fmac_f32_e32 v66, v180, v40
	v_fmac_f32_e32 v67, v181, v41
	v_fmac_f32_e32 v66, v182, v42
	v_fmac_f32_e32 v67, v183, v43
	ds_read_b128 v[180:183], v105 offset:46752
	s_waitcnt lgkmcnt(11)
	v_fmac_f32_e32 v66, v136, v44
	v_fmac_f32_e32 v67, v137, v45
	v_fmac_f32_e32 v66, v138, v46
	v_sub_f32_e32 v47, v47, v66
	v_sub_f32_e32 v47, v47, v67
	ds_read_b128 v[136:139], v105 offset:46848
	s_waitcnt lgkmcnt(11)
	v_mul_f32_e32 v66, v140, v0
	v_mul_f32_e32 v67, v141, v4
	v_fmac_f32_e32 v66, v142, v5
	v_fmac_f32_e32 v67, v143, v6
	ds_read_b128 v[140:143], v105 offset:46864
	s_waitcnt lgkmcnt(11)
	v_fmac_f32_e32 v66, v144, v7
	v_fmac_f32_e32 v67, v145, v8
	v_fmac_f32_e32 v66, v146, v9
	v_fmac_f32_e32 v67, v147, v10
	ds_read_b128 v[144:147], v105 offset:46880
	s_waitcnt lgkmcnt(11)
	v_fmac_f32_e32 v66, v148, v11
	v_fmac_f32_e32 v67, v149, v12
	v_fmac_f32_e32 v66, v150, v13
	v_fmac_f32_e32 v67, v151, v14
	ds_read_b128 v[148:151], v105 offset:46896
	s_waitcnt lgkmcnt(11)
	v_fmac_f32_e32 v66, v152, v15
	v_fmac_f32_e32 v67, v153, v16
	v_fmac_f32_e32 v66, v154, v17
	v_fmac_f32_e32 v67, v155, v18
	ds_read_b128 v[152:155], v105 offset:46912
	s_waitcnt lgkmcnt(11)
	v_fmac_f32_e32 v66, v156, v20
	v_fmac_f32_e32 v67, v157, v21
	v_fmac_f32_e32 v66, v158, v22
	v_fmac_f32_e32 v67, v159, v23
	ds_read_b128 v[156:159], v105 offset:46928
	s_waitcnt lgkmcnt(11)
	v_fmac_f32_e32 v66, v160, v24
	v_fmac_f32_e32 v67, v161, v25
	v_fmac_f32_e32 v66, v162, v26
	v_fmac_f32_e32 v67, v163, v27
	ds_read_b128 v[160:163], v105 offset:46944
	s_waitcnt lgkmcnt(11)
	v_fmac_f32_e32 v66, v164, v28
	v_fmac_f32_e32 v67, v165, v29
	v_fmac_f32_e32 v66, v166, v30
	v_fmac_f32_e32 v67, v167, v31
	ds_read_b128 v[164:167], v105 offset:46960
	s_waitcnt lgkmcnt(11)
	v_fmac_f32_e32 v66, v168, v32
	v_fmac_f32_e32 v67, v169, v33
	v_fmac_f32_e32 v66, v170, v34
	v_fmac_f32_e32 v67, v171, v35
	ds_read_b128 v[168:171], v105 offset:46976
	s_waitcnt lgkmcnt(11)
	v_fmac_f32_e32 v66, v172, v36
	v_fmac_f32_e32 v67, v173, v37
	v_fmac_f32_e32 v66, v174, v38
	v_fmac_f32_e32 v67, v175, v39
	ds_read_b128 v[172:175], v105 offset:46992
	s_waitcnt lgkmcnt(11)
	v_fmac_f32_e32 v66, v176, v40
	v_fmac_f32_e32 v67, v177, v41
	v_fmac_f32_e32 v66, v178, v42
	v_fmac_f32_e32 v67, v179, v43
	ds_read_b128 v[176:179], v105 offset:47008
	s_waitcnt lgkmcnt(11)
	v_fmac_f32_e32 v66, v180, v44
	v_fmac_f32_e32 v67, v181, v45
	v_fmac_f32_e32 v66, v182, v46
	v_fmac_f32_e32 v67, v183, v47
	v_sub_f32_e32 v48, v48, v66
	v_sub_f32_e32 v48, v48, v67
	ds_read_b128 v[180:183], v105 offset:47024
	s_waitcnt lgkmcnt(11)
	v_mul_f32_e32 v66, v136, v0
	v_mul_f32_e32 v67, v137, v4
	v_fmac_f32_e32 v66, v138, v5
	v_fmac_f32_e32 v67, v139, v6
	ds_read_b128 v[136:139], v105 offset:47104
	s_waitcnt lgkmcnt(11)
	v_fmac_f32_e32 v66, v140, v7
	v_fmac_f32_e32 v67, v141, v8
	v_fmac_f32_e32 v66, v142, v9
	v_fmac_f32_e32 v67, v143, v10
	ds_read_b128 v[140:143], v105 offset:47120
	s_waitcnt lgkmcnt(11)
	v_fmac_f32_e32 v66, v144, v11
	v_fmac_f32_e32 v67, v145, v12
	v_fmac_f32_e32 v66, v146, v13
	v_fmac_f32_e32 v67, v147, v14
	ds_read_b128 v[144:147], v105 offset:47136
	s_waitcnt lgkmcnt(11)
	v_fmac_f32_e32 v66, v148, v15
	v_fmac_f32_e32 v67, v149, v16
	v_fmac_f32_e32 v66, v150, v17
	v_fmac_f32_e32 v67, v151, v18
	ds_read_b128 v[148:151], v105 offset:47152
	s_waitcnt lgkmcnt(11)
	v_fmac_f32_e32 v66, v152, v20
	v_fmac_f32_e32 v67, v153, v21
	v_fmac_f32_e32 v66, v154, v22
	v_fmac_f32_e32 v67, v155, v23
	ds_read_b128 v[152:155], v105 offset:47168
	s_waitcnt lgkmcnt(11)
	v_fmac_f32_e32 v66, v156, v24
	v_fmac_f32_e32 v67, v157, v25
	v_fmac_f32_e32 v66, v158, v26
	v_fmac_f32_e32 v67, v159, v27
	ds_read_b128 v[156:159], v105 offset:47184
	s_waitcnt lgkmcnt(11)
	v_fmac_f32_e32 v66, v160, v28
	v_fmac_f32_e32 v67, v161, v29
	v_fmac_f32_e32 v66, v162, v30
	v_fmac_f32_e32 v67, v163, v31
	ds_read_b128 v[160:163], v105 offset:47200
	s_waitcnt lgkmcnt(11)
	v_fmac_f32_e32 v66, v164, v32
	v_fmac_f32_e32 v67, v165, v33
	v_fmac_f32_e32 v66, v166, v34
	v_fmac_f32_e32 v67, v167, v35
	ds_read_b128 v[164:167], v105 offset:47216
	s_waitcnt lgkmcnt(11)
	v_fmac_f32_e32 v66, v168, v36
	v_fmac_f32_e32 v67, v169, v37
	v_fmac_f32_e32 v66, v170, v38
	v_fmac_f32_e32 v67, v171, v39
	ds_read_b128 v[168:171], v105 offset:47232
	s_waitcnt lgkmcnt(11)
	v_fmac_f32_e32 v66, v172, v40
	v_fmac_f32_e32 v67, v173, v41
	v_fmac_f32_e32 v66, v174, v42
	v_fmac_f32_e32 v67, v175, v43
	ds_read_b128 v[172:175], v105 offset:47248
	s_waitcnt lgkmcnt(11)
	v_fmac_f32_e32 v66, v176, v44
	v_fmac_f32_e32 v67, v177, v45
	v_fmac_f32_e32 v66, v178, v46
	v_fmac_f32_e32 v67, v179, v47
	ds_read_b128 v[176:179], v105 offset:47264
	s_waitcnt lgkmcnt(11)
	v_fmac_f32_e32 v66, v180, v48
	v_sub_f32_e32 v49, v49, v66
	v_sub_f32_e32 v49, v49, v67
	ds_read_b128 v[180:183], v105 offset:47280
	s_waitcnt lgkmcnt(11)
	v_mul_f32_e32 v66, v136, v0
	v_mul_f32_e32 v67, v137, v4
	v_fmac_f32_e32 v66, v138, v5
	v_fmac_f32_e32 v67, v139, v6
	ds_read_b128 v[136:139], v105 offset:47360
	s_waitcnt lgkmcnt(11)
	v_fmac_f32_e32 v66, v140, v7
	v_fmac_f32_e32 v67, v141, v8
	v_fmac_f32_e32 v66, v142, v9
	v_fmac_f32_e32 v67, v143, v10
	ds_read_b128 v[140:143], v105 offset:47376
	s_waitcnt lgkmcnt(11)
	v_fmac_f32_e32 v66, v144, v11
	v_fmac_f32_e32 v67, v145, v12
	v_fmac_f32_e32 v66, v146, v13
	v_fmac_f32_e32 v67, v147, v14
	ds_read_b128 v[144:147], v105 offset:47392
	s_waitcnt lgkmcnt(11)
	v_fmac_f32_e32 v66, v148, v15
	v_fmac_f32_e32 v67, v149, v16
	v_fmac_f32_e32 v66, v150, v17
	v_fmac_f32_e32 v67, v151, v18
	ds_read_b128 v[148:151], v105 offset:47408
	s_waitcnt lgkmcnt(11)
	v_fmac_f32_e32 v66, v152, v20
	v_fmac_f32_e32 v67, v153, v21
	v_fmac_f32_e32 v66, v154, v22
	v_fmac_f32_e32 v67, v155, v23
	ds_read_b128 v[152:155], v105 offset:47424
	s_waitcnt lgkmcnt(11)
	v_fmac_f32_e32 v66, v156, v24
	v_fmac_f32_e32 v67, v157, v25
	v_fmac_f32_e32 v66, v158, v26
	v_fmac_f32_e32 v67, v159, v27
	ds_read_b128 v[156:159], v105 offset:47440
	s_waitcnt lgkmcnt(11)
	v_fmac_f32_e32 v66, v160, v28
	v_fmac_f32_e32 v67, v161, v29
	v_fmac_f32_e32 v66, v162, v30
	v_fmac_f32_e32 v67, v163, v31
	ds_read_b128 v[160:163], v105 offset:47456
	s_waitcnt lgkmcnt(11)
	v_fmac_f32_e32 v66, v164, v32
	v_fmac_f32_e32 v67, v165, v33
	v_fmac_f32_e32 v66, v166, v34
	v_fmac_f32_e32 v67, v167, v35
	ds_read_b128 v[164:167], v105 offset:47472
	s_waitcnt lgkmcnt(11)
	v_fmac_f32_e32 v66, v168, v36
	v_fmac_f32_e32 v67, v169, v37
	v_fmac_f32_e32 v66, v170, v38
	v_fmac_f32_e32 v67, v171, v39
	ds_read_b128 v[168:171], v105 offset:47488
	s_waitcnt lgkmcnt(11)
	v_fmac_f32_e32 v66, v172, v40
	v_fmac_f32_e32 v67, v173, v41
	v_fmac_f32_e32 v66, v174, v42
	v_fmac_f32_e32 v67, v175, v43
	ds_read_b128 v[172:175], v105 offset:47504
	s_waitcnt lgkmcnt(11)
	v_fmac_f32_e32 v66, v176, v44
	v_fmac_f32_e32 v67, v177, v45
	v_fmac_f32_e32 v66, v178, v46
	v_fmac_f32_e32 v67, v179, v47
	ds_read_b128 v[176:179], v105 offset:47520
	s_waitcnt lgkmcnt(11)
	v_fmac_f32_e32 v66, v180, v48
	v_fmac_f32_e32 v67, v181, v49
	v_sub_f32_e32 v50, v50, v66
	v_sub_f32_e32 v50, v50, v67
	ds_read_b128 v[180:183], v105 offset:47536
	s_waitcnt lgkmcnt(11)
	v_mul_f32_e32 v66, v136, v0
	v_mul_f32_e32 v67, v137, v4
	v_fmac_f32_e32 v66, v138, v5
	v_fmac_f32_e32 v67, v139, v6
	ds_read_b128 v[136:139], v105 offset:47616
	s_waitcnt lgkmcnt(11)
	v_fmac_f32_e32 v66, v140, v7
	v_fmac_f32_e32 v67, v141, v8
	v_fmac_f32_e32 v66, v142, v9
	v_fmac_f32_e32 v67, v143, v10
	ds_read_b128 v[140:143], v105 offset:47632
	s_waitcnt lgkmcnt(11)
	v_fmac_f32_e32 v66, v144, v11
	v_fmac_f32_e32 v67, v145, v12
	v_fmac_f32_e32 v66, v146, v13
	v_fmac_f32_e32 v67, v147, v14
	ds_read_b128 v[144:147], v105 offset:47648
	s_waitcnt lgkmcnt(11)
	v_fmac_f32_e32 v66, v148, v15
	v_fmac_f32_e32 v67, v149, v16
	v_fmac_f32_e32 v66, v150, v17
	v_fmac_f32_e32 v67, v151, v18
	ds_read_b128 v[148:151], v105 offset:47664
	s_waitcnt lgkmcnt(11)
	v_fmac_f32_e32 v66, v152, v20
	v_fmac_f32_e32 v67, v153, v21
	v_fmac_f32_e32 v66, v154, v22
	v_fmac_f32_e32 v67, v155, v23
	ds_read_b128 v[152:155], v105 offset:47680
	s_waitcnt lgkmcnt(11)
	v_fmac_f32_e32 v66, v156, v24
	v_fmac_f32_e32 v67, v157, v25
	v_fmac_f32_e32 v66, v158, v26
	v_fmac_f32_e32 v67, v159, v27
	ds_read_b128 v[156:159], v105 offset:47696
	s_waitcnt lgkmcnt(11)
	v_fmac_f32_e32 v66, v160, v28
	v_fmac_f32_e32 v67, v161, v29
	v_fmac_f32_e32 v66, v162, v30
	v_fmac_f32_e32 v67, v163, v31
	ds_read_b128 v[160:163], v105 offset:47712
	s_waitcnt lgkmcnt(11)
	v_fmac_f32_e32 v66, v164, v32
	v_fmac_f32_e32 v67, v165, v33
	v_fmac_f32_e32 v66, v166, v34
	v_fmac_f32_e32 v67, v167, v35
	ds_read_b128 v[164:167], v105 offset:47728
	s_waitcnt lgkmcnt(11)
	v_fmac_f32_e32 v66, v168, v36
	v_fmac_f32_e32 v67, v169, v37
	v_fmac_f32_e32 v66, v170, v38
	v_fmac_f32_e32 v67, v171, v39
	ds_read_b128 v[168:171], v105 offset:47744
	s_waitcnt lgkmcnt(11)
	v_fmac_f32_e32 v66, v172, v40
	v_fmac_f32_e32 v67, v173, v41
	v_fmac_f32_e32 v66, v174, v42
	v_fmac_f32_e32 v67, v175, v43
	ds_read_b128 v[172:175], v105 offset:47760
	s_waitcnt lgkmcnt(11)
	v_fmac_f32_e32 v66, v176, v44
	v_fmac_f32_e32 v67, v177, v45
	v_fmac_f32_e32 v66, v178, v46
	v_fmac_f32_e32 v67, v179, v47
	ds_read_b128 v[176:179], v105 offset:47776
	s_waitcnt lgkmcnt(11)
	v_fmac_f32_e32 v66, v180, v48
	v_fmac_f32_e32 v67, v181, v49
	v_fmac_f32_e32 v66, v182, v50
	v_sub_f32_e32 v51, v51, v66
	v_sub_f32_e32 v51, v51, v67
	ds_read_b128 v[180:183], v105 offset:47792
	s_waitcnt lgkmcnt(11)
	v_mul_f32_e32 v66, v136, v0
	v_mul_f32_e32 v67, v137, v4
	v_fmac_f32_e32 v66, v138, v5
	v_fmac_f32_e32 v67, v139, v6
	ds_read_b128 v[136:139], v105 offset:47872
	s_waitcnt lgkmcnt(11)
	v_fmac_f32_e32 v66, v140, v7
	v_fmac_f32_e32 v67, v141, v8
	v_fmac_f32_e32 v66, v142, v9
	v_fmac_f32_e32 v67, v143, v10
	ds_read_b128 v[140:143], v105 offset:47888
	s_waitcnt lgkmcnt(11)
	v_fmac_f32_e32 v66, v144, v11
	v_fmac_f32_e32 v67, v145, v12
	v_fmac_f32_e32 v66, v146, v13
	v_fmac_f32_e32 v67, v147, v14
	ds_read_b128 v[144:147], v105 offset:47904
	s_waitcnt lgkmcnt(11)
	v_fmac_f32_e32 v66, v148, v15
	v_fmac_f32_e32 v67, v149, v16
	v_fmac_f32_e32 v66, v150, v17
	v_fmac_f32_e32 v67, v151, v18
	ds_read_b128 v[148:151], v105 offset:47920
	s_waitcnt lgkmcnt(11)
	v_fmac_f32_e32 v66, v152, v20
	v_fmac_f32_e32 v67, v153, v21
	v_fmac_f32_e32 v66, v154, v22
	v_fmac_f32_e32 v67, v155, v23
	ds_read_b128 v[152:155], v105 offset:47936
	s_waitcnt lgkmcnt(11)
	v_fmac_f32_e32 v66, v156, v24
	v_fmac_f32_e32 v67, v157, v25
	v_fmac_f32_e32 v66, v158, v26
	v_fmac_f32_e32 v67, v159, v27
	ds_read_b128 v[156:159], v105 offset:47952
	s_waitcnt lgkmcnt(11)
	v_fmac_f32_e32 v66, v160, v28
	v_fmac_f32_e32 v67, v161, v29
	v_fmac_f32_e32 v66, v162, v30
	v_fmac_f32_e32 v67, v163, v31
	ds_read_b128 v[160:163], v105 offset:47968
	s_waitcnt lgkmcnt(11)
	v_fmac_f32_e32 v66, v164, v32
	v_fmac_f32_e32 v67, v165, v33
	v_fmac_f32_e32 v66, v166, v34
	v_fmac_f32_e32 v67, v167, v35
	ds_read_b128 v[164:167], v105 offset:47984
	s_waitcnt lgkmcnt(11)
	v_fmac_f32_e32 v66, v168, v36
	v_fmac_f32_e32 v67, v169, v37
	v_fmac_f32_e32 v66, v170, v38
	v_fmac_f32_e32 v67, v171, v39
	ds_read_b128 v[168:171], v105 offset:48000
	s_waitcnt lgkmcnt(11)
	v_fmac_f32_e32 v66, v172, v40
	v_fmac_f32_e32 v67, v173, v41
	v_fmac_f32_e32 v66, v174, v42
	v_fmac_f32_e32 v67, v175, v43
	ds_read_b128 v[172:175], v105 offset:48016
	s_waitcnt lgkmcnt(11)
	v_fmac_f32_e32 v66, v176, v44
	v_fmac_f32_e32 v67, v177, v45
	v_fmac_f32_e32 v66, v178, v46
	v_fmac_f32_e32 v67, v179, v47
	ds_read_b128 v[176:179], v105 offset:48032
	s_waitcnt lgkmcnt(11)
	v_fmac_f32_e32 v66, v180, v48
	v_fmac_f32_e32 v67, v181, v49
	v_fmac_f32_e32 v66, v182, v50
	v_fmac_f32_e32 v67, v183, v51
	v_sub_f32_e32 v52, v52, v66
	v_sub_f32_e32 v52, v52, v67
	ds_read_b128 v[180:183], v105 offset:48048
	s_waitcnt lgkmcnt(11)
	v_mul_f32_e32 v66, v136, v0
	v_mul_f32_e32 v67, v137, v4
	v_fmac_f32_e32 v66, v138, v5
	v_fmac_f32_e32 v67, v139, v6
	ds_read_b128 v[136:139], v105 offset:48064
	s_waitcnt lgkmcnt(11)
	v_fmac_f32_e32 v66, v140, v7
	v_fmac_f32_e32 v67, v141, v8
	v_fmac_f32_e32 v66, v142, v9
	v_fmac_f32_e32 v67, v143, v10
	ds_read_b128 v[140:143], v105 offset:48128
	s_waitcnt lgkmcnt(11)
	v_fmac_f32_e32 v66, v144, v11
	v_fmac_f32_e32 v67, v145, v12
	v_fmac_f32_e32 v66, v146, v13
	v_fmac_f32_e32 v67, v147, v14
	ds_read_b128 v[144:147], v105 offset:48144
	s_waitcnt lgkmcnt(11)
	v_fmac_f32_e32 v66, v148, v15
	v_fmac_f32_e32 v67, v149, v16
	v_fmac_f32_e32 v66, v150, v17
	v_fmac_f32_e32 v67, v151, v18
	ds_read_b128 v[148:151], v105 offset:48160
	s_waitcnt lgkmcnt(11)
	v_fmac_f32_e32 v66, v152, v20
	v_fmac_f32_e32 v67, v153, v21
	v_fmac_f32_e32 v66, v154, v22
	v_fmac_f32_e32 v67, v155, v23
	ds_read_b128 v[152:155], v105 offset:48176
	s_waitcnt lgkmcnt(11)
	v_fmac_f32_e32 v66, v156, v24
	v_fmac_f32_e32 v67, v157, v25
	v_fmac_f32_e32 v66, v158, v26
	v_fmac_f32_e32 v67, v159, v27
	ds_read_b128 v[156:159], v105 offset:48192
	s_waitcnt lgkmcnt(11)
	v_fmac_f32_e32 v66, v160, v28
	v_fmac_f32_e32 v67, v161, v29
	v_fmac_f32_e32 v66, v162, v30
	v_fmac_f32_e32 v67, v163, v31
	ds_read_b128 v[160:163], v105 offset:48208
	s_waitcnt lgkmcnt(11)
	v_fmac_f32_e32 v66, v164, v32
	v_fmac_f32_e32 v67, v165, v33
	v_fmac_f32_e32 v66, v166, v34
	v_fmac_f32_e32 v67, v167, v35
	ds_read_b128 v[164:167], v105 offset:48224
	s_waitcnt lgkmcnt(11)
	v_fmac_f32_e32 v66, v168, v36
	v_fmac_f32_e32 v67, v169, v37
	v_fmac_f32_e32 v66, v170, v38
	v_fmac_f32_e32 v67, v171, v39
	ds_read_b128 v[168:171], v105 offset:48240
	s_waitcnt lgkmcnt(11)
	v_fmac_f32_e32 v66, v172, v40
	v_fmac_f32_e32 v67, v173, v41
	v_fmac_f32_e32 v66, v174, v42
	v_fmac_f32_e32 v67, v175, v43
	ds_read_b128 v[172:175], v105 offset:48256
	s_waitcnt lgkmcnt(11)
	v_fmac_f32_e32 v66, v176, v44
	v_fmac_f32_e32 v67, v177, v45
	v_fmac_f32_e32 v66, v178, v46
	v_fmac_f32_e32 v67, v179, v47
	ds_read_b128 v[176:179], v105 offset:48272
	s_waitcnt lgkmcnt(11)
	v_fmac_f32_e32 v66, v180, v48
	v_fmac_f32_e32 v67, v181, v49
	v_fmac_f32_e32 v66, v182, v50
	v_fmac_f32_e32 v67, v183, v51
	ds_read_b128 v[180:183], v105 offset:48288
	s_waitcnt lgkmcnt(11)
	v_fmac_f32_e32 v66, v136, v52
	v_sub_f32_e32 v53, v53, v66
	v_sub_f32_e32 v53, v53, v67
	ds_read_b128 v[136:139], v105 offset:48304
	s_waitcnt lgkmcnt(11)
	v_mul_f32_e32 v66, v140, v0
	v_mul_f32_e32 v67, v141, v4
	v_fmac_f32_e32 v66, v142, v5
	v_fmac_f32_e32 v67, v143, v6
	ds_read_b128 v[140:143], v105 offset:48320
	s_waitcnt lgkmcnt(11)
	v_fmac_f32_e32 v66, v144, v7
	v_fmac_f32_e32 v67, v145, v8
	v_fmac_f32_e32 v66, v146, v9
	v_fmac_f32_e32 v67, v147, v10
	ds_read_b128 v[144:147], v105 offset:48384
	s_waitcnt lgkmcnt(11)
	v_fmac_f32_e32 v66, v148, v11
	v_fmac_f32_e32 v67, v149, v12
	v_fmac_f32_e32 v66, v150, v13
	v_fmac_f32_e32 v67, v151, v14
	ds_read_b128 v[148:151], v105 offset:48400
	s_waitcnt lgkmcnt(11)
	v_fmac_f32_e32 v66, v152, v15
	v_fmac_f32_e32 v67, v153, v16
	v_fmac_f32_e32 v66, v154, v17
	v_fmac_f32_e32 v67, v155, v18
	ds_read_b128 v[152:155], v105 offset:48416
	s_waitcnt lgkmcnt(11)
	v_fmac_f32_e32 v66, v156, v20
	v_fmac_f32_e32 v67, v157, v21
	v_fmac_f32_e32 v66, v158, v22
	v_fmac_f32_e32 v67, v159, v23
	ds_read_b128 v[156:159], v105 offset:48432
	s_waitcnt lgkmcnt(11)
	v_fmac_f32_e32 v66, v160, v24
	v_fmac_f32_e32 v67, v161, v25
	v_fmac_f32_e32 v66, v162, v26
	v_fmac_f32_e32 v67, v163, v27
	ds_read_b128 v[160:163], v105 offset:48448
	s_waitcnt lgkmcnt(11)
	v_fmac_f32_e32 v66, v164, v28
	v_fmac_f32_e32 v67, v165, v29
	v_fmac_f32_e32 v66, v166, v30
	v_fmac_f32_e32 v67, v167, v31
	ds_read_b128 v[164:167], v105 offset:48464
	s_waitcnt lgkmcnt(11)
	v_fmac_f32_e32 v66, v168, v32
	v_fmac_f32_e32 v67, v169, v33
	v_fmac_f32_e32 v66, v170, v34
	v_fmac_f32_e32 v67, v171, v35
	ds_read_b128 v[168:171], v105 offset:48480
	s_waitcnt lgkmcnt(11)
	v_fmac_f32_e32 v66, v172, v36
	v_fmac_f32_e32 v67, v173, v37
	v_fmac_f32_e32 v66, v174, v38
	v_fmac_f32_e32 v67, v175, v39
	ds_read_b128 v[172:175], v105 offset:48496
	s_waitcnt lgkmcnt(11)
	v_fmac_f32_e32 v66, v176, v40
	v_fmac_f32_e32 v67, v177, v41
	v_fmac_f32_e32 v66, v178, v42
	v_fmac_f32_e32 v67, v179, v43
	ds_read_b128 v[176:179], v105 offset:48512
	s_waitcnt lgkmcnt(11)
	v_fmac_f32_e32 v66, v180, v44
	v_fmac_f32_e32 v67, v181, v45
	v_fmac_f32_e32 v66, v182, v46
	v_fmac_f32_e32 v67, v183, v47
	ds_read_b128 v[180:183], v105 offset:48528
	s_waitcnt lgkmcnt(11)
	v_fmac_f32_e32 v66, v136, v48
	v_fmac_f32_e32 v67, v137, v49
	v_fmac_f32_e32 v66, v138, v50
	v_fmac_f32_e32 v67, v139, v51
	ds_read_b128 v[136:139], v105 offset:48544
	s_waitcnt lgkmcnt(11)
	v_fmac_f32_e32 v66, v140, v52
	v_fmac_f32_e32 v67, v141, v53
	v_sub_f32_e32 v54, v54, v66
	v_sub_f32_e32 v54, v54, v67
	ds_read_b128 v[140:143], v105 offset:48560
	s_waitcnt lgkmcnt(11)
	v_mul_f32_e32 v66, v144, v0
	v_mul_f32_e32 v67, v145, v4
	v_fmac_f32_e32 v66, v146, v5
	v_fmac_f32_e32 v67, v147, v6
	ds_read_b128 v[144:147], v105 offset:48576
	s_waitcnt lgkmcnt(11)
	v_fmac_f32_e32 v66, v148, v7
	v_fmac_f32_e32 v67, v149, v8
	v_fmac_f32_e32 v66, v150, v9
	v_fmac_f32_e32 v67, v151, v10
	ds_read_b128 v[148:151], v105 offset:48640
	s_waitcnt lgkmcnt(11)
	v_fmac_f32_e32 v66, v152, v11
	v_fmac_f32_e32 v67, v153, v12
	v_fmac_f32_e32 v66, v154, v13
	v_fmac_f32_e32 v67, v155, v14
	ds_read_b128 v[152:155], v105 offset:48656
	s_waitcnt lgkmcnt(11)
	v_fmac_f32_e32 v66, v156, v15
	v_fmac_f32_e32 v67, v157, v16
	v_fmac_f32_e32 v66, v158, v17
	v_fmac_f32_e32 v67, v159, v18
	ds_read_b128 v[156:159], v105 offset:48672
	s_waitcnt lgkmcnt(11)
	v_fmac_f32_e32 v66, v160, v20
	v_fmac_f32_e32 v67, v161, v21
	v_fmac_f32_e32 v66, v162, v22
	v_fmac_f32_e32 v67, v163, v23
	ds_read_b128 v[160:163], v105 offset:48688
	s_waitcnt lgkmcnt(11)
	v_fmac_f32_e32 v66, v164, v24
	v_fmac_f32_e32 v67, v165, v25
	v_fmac_f32_e32 v66, v166, v26
	v_fmac_f32_e32 v67, v167, v27
	ds_read_b128 v[164:167], v105 offset:48704
	s_waitcnt lgkmcnt(11)
	v_fmac_f32_e32 v66, v168, v28
	v_fmac_f32_e32 v67, v169, v29
	v_fmac_f32_e32 v66, v170, v30
	v_fmac_f32_e32 v67, v171, v31
	ds_read_b128 v[168:171], v105 offset:48720
	s_waitcnt lgkmcnt(11)
	v_fmac_f32_e32 v66, v172, v32
	v_fmac_f32_e32 v67, v173, v33
	v_fmac_f32_e32 v66, v174, v34
	v_fmac_f32_e32 v67, v175, v35
	ds_read_b128 v[172:175], v105 offset:48736
	s_waitcnt lgkmcnt(11)
	v_fmac_f32_e32 v66, v176, v36
	v_fmac_f32_e32 v67, v177, v37
	v_fmac_f32_e32 v66, v178, v38
	v_fmac_f32_e32 v67, v179, v39
	ds_read_b128 v[176:179], v105 offset:48752
	s_waitcnt lgkmcnt(11)
	v_fmac_f32_e32 v66, v180, v40
	v_fmac_f32_e32 v67, v181, v41
	v_fmac_f32_e32 v66, v182, v42
	v_fmac_f32_e32 v67, v183, v43
	ds_read_b128 v[180:183], v105 offset:48768
	s_waitcnt lgkmcnt(11)
	v_fmac_f32_e32 v66, v136, v44
	v_fmac_f32_e32 v67, v137, v45
	v_fmac_f32_e32 v66, v138, v46
	v_fmac_f32_e32 v67, v139, v47
	ds_read_b128 v[136:139], v105 offset:48784
	s_waitcnt lgkmcnt(11)
	v_fmac_f32_e32 v66, v140, v48
	v_fmac_f32_e32 v67, v141, v49
	v_fmac_f32_e32 v66, v142, v50
	v_fmac_f32_e32 v67, v143, v51
	ds_read_b128 v[140:143], v105 offset:48800
	s_waitcnt lgkmcnt(11)
	v_fmac_f32_e32 v66, v144, v52
	v_fmac_f32_e32 v67, v145, v53
	v_fmac_f32_e32 v66, v146, v54
	v_sub_f32_e32 v55, v55, v66
	v_sub_f32_e32 v55, v55, v67
	ds_read_b128 v[144:147], v105 offset:48816
	s_waitcnt lgkmcnt(11)
	v_mul_f32_e32 v66, v148, v0
	v_mul_f32_e32 v67, v149, v4
	v_fmac_f32_e32 v66, v150, v5
	v_fmac_f32_e32 v67, v151, v6
	ds_read_b128 v[148:151], v105 offset:48832
	s_waitcnt lgkmcnt(11)
	v_fmac_f32_e32 v66, v152, v7
	v_fmac_f32_e32 v67, v153, v8
	v_fmac_f32_e32 v66, v154, v9
	v_fmac_f32_e32 v67, v155, v10
	ds_read_b128 v[152:155], v105 offset:48896
	s_waitcnt lgkmcnt(11)
	v_fmac_f32_e32 v66, v156, v11
	v_fmac_f32_e32 v67, v157, v12
	v_fmac_f32_e32 v66, v158, v13
	v_fmac_f32_e32 v67, v159, v14
	ds_read_b128 v[156:159], v105 offset:48912
	s_waitcnt lgkmcnt(11)
	v_fmac_f32_e32 v66, v160, v15
	v_fmac_f32_e32 v67, v161, v16
	v_fmac_f32_e32 v66, v162, v17
	v_fmac_f32_e32 v67, v163, v18
	ds_read_b128 v[160:163], v105 offset:48928
	s_waitcnt lgkmcnt(11)
	v_fmac_f32_e32 v66, v164, v20
	v_fmac_f32_e32 v67, v165, v21
	v_fmac_f32_e32 v66, v166, v22
	v_fmac_f32_e32 v67, v167, v23
	ds_read_b128 v[164:167], v105 offset:48944
	s_waitcnt lgkmcnt(11)
	v_fmac_f32_e32 v66, v168, v24
	v_fmac_f32_e32 v67, v169, v25
	v_fmac_f32_e32 v66, v170, v26
	v_fmac_f32_e32 v67, v171, v27
	ds_read_b128 v[168:171], v105 offset:48960
	s_waitcnt lgkmcnt(11)
	v_fmac_f32_e32 v66, v172, v28
	v_fmac_f32_e32 v67, v173, v29
	v_fmac_f32_e32 v66, v174, v30
	v_fmac_f32_e32 v67, v175, v31
	ds_read_b128 v[172:175], v105 offset:48976
	s_waitcnt lgkmcnt(11)
	v_fmac_f32_e32 v66, v176, v32
	v_fmac_f32_e32 v67, v177, v33
	v_fmac_f32_e32 v66, v178, v34
	v_fmac_f32_e32 v67, v179, v35
	ds_read_b128 v[176:179], v105 offset:48992
	s_waitcnt lgkmcnt(11)
	v_fmac_f32_e32 v66, v180, v36
	v_fmac_f32_e32 v67, v181, v37
	v_fmac_f32_e32 v66, v182, v38
	v_fmac_f32_e32 v67, v183, v39
	ds_read_b128 v[180:183], v105 offset:49008
	s_waitcnt lgkmcnt(11)
	v_fmac_f32_e32 v66, v136, v40
	v_fmac_f32_e32 v67, v137, v41
	v_fmac_f32_e32 v66, v138, v42
	v_fmac_f32_e32 v67, v139, v43
	ds_read_b128 v[136:139], v105 offset:49024
	s_waitcnt lgkmcnt(11)
	v_fmac_f32_e32 v66, v140, v44
	v_fmac_f32_e32 v67, v141, v45
	v_fmac_f32_e32 v66, v142, v46
	v_fmac_f32_e32 v67, v143, v47
	ds_read_b128 v[140:143], v105 offset:49040
	s_waitcnt lgkmcnt(11)
	v_fmac_f32_e32 v66, v144, v48
	v_fmac_f32_e32 v67, v145, v49
	v_fmac_f32_e32 v66, v146, v50
	v_fmac_f32_e32 v67, v147, v51
	ds_read_b128 v[144:147], v105 offset:49056
	s_waitcnt lgkmcnt(11)
	v_fmac_f32_e32 v66, v148, v52
	v_fmac_f32_e32 v67, v149, v53
	v_fmac_f32_e32 v66, v150, v54
	v_fmac_f32_e32 v67, v151, v55
	v_sub_f32_e32 v56, v56, v66
	v_sub_f32_e32 v56, v56, v67
	ds_read_b128 v[148:151], v105 offset:49072
	s_waitcnt lgkmcnt(11)
	v_mul_f32_e32 v66, v152, v0
	v_mul_f32_e32 v67, v153, v4
	v_fmac_f32_e32 v66, v154, v5
	v_fmac_f32_e32 v67, v155, v6
	ds_read_b128 v[152:155], v105 offset:49088
	s_waitcnt lgkmcnt(11)
	v_fmac_f32_e32 v66, v156, v7
	v_fmac_f32_e32 v67, v157, v8
	v_fmac_f32_e32 v66, v158, v9
	v_fmac_f32_e32 v67, v159, v10
	ds_read_b128 v[156:159], v105 offset:49104
	s_waitcnt lgkmcnt(11)
	v_fmac_f32_e32 v66, v160, v11
	v_fmac_f32_e32 v67, v161, v12
	v_fmac_f32_e32 v66, v162, v13
	v_fmac_f32_e32 v67, v163, v14
	ds_read_b128 v[160:163], v105 offset:49152
	s_waitcnt lgkmcnt(11)
	v_fmac_f32_e32 v66, v164, v15
	v_fmac_f32_e32 v67, v165, v16
	v_fmac_f32_e32 v66, v166, v17
	v_fmac_f32_e32 v67, v167, v18
	ds_read_b128 v[164:167], v105 offset:49168
	s_waitcnt lgkmcnt(11)
	v_fmac_f32_e32 v66, v168, v20
	v_fmac_f32_e32 v67, v169, v21
	v_fmac_f32_e32 v66, v170, v22
	v_fmac_f32_e32 v67, v171, v23
	ds_read_b128 v[168:171], v105 offset:49184
	s_waitcnt lgkmcnt(11)
	v_fmac_f32_e32 v66, v172, v24
	v_fmac_f32_e32 v67, v173, v25
	v_fmac_f32_e32 v66, v174, v26
	v_fmac_f32_e32 v67, v175, v27
	ds_read_b128 v[172:175], v105 offset:49200
	s_waitcnt lgkmcnt(11)
	v_fmac_f32_e32 v66, v176, v28
	v_fmac_f32_e32 v67, v177, v29
	v_fmac_f32_e32 v66, v178, v30
	v_fmac_f32_e32 v67, v179, v31
	ds_read_b128 v[176:179], v105 offset:49216
	s_waitcnt lgkmcnt(11)
	v_fmac_f32_e32 v66, v180, v32
	v_fmac_f32_e32 v67, v181, v33
	v_fmac_f32_e32 v66, v182, v34
	v_fmac_f32_e32 v67, v183, v35
	ds_read_b128 v[180:183], v105 offset:49232
	s_waitcnt lgkmcnt(11)
	v_fmac_f32_e32 v66, v136, v36
	v_fmac_f32_e32 v67, v137, v37
	v_fmac_f32_e32 v66, v138, v38
	v_fmac_f32_e32 v67, v139, v39
	ds_read_b128 v[136:139], v105 offset:49248
	s_waitcnt lgkmcnt(11)
	v_fmac_f32_e32 v66, v140, v40
	v_fmac_f32_e32 v67, v141, v41
	v_fmac_f32_e32 v66, v142, v42
	v_fmac_f32_e32 v67, v143, v43
	ds_read_b128 v[140:143], v105 offset:49264
	s_waitcnt lgkmcnt(11)
	v_fmac_f32_e32 v66, v144, v44
	v_fmac_f32_e32 v67, v145, v45
	v_fmac_f32_e32 v66, v146, v46
	v_fmac_f32_e32 v67, v147, v47
	ds_read_b128 v[144:147], v105 offset:49280
	s_waitcnt lgkmcnt(11)
	v_fmac_f32_e32 v66, v148, v48
	v_fmac_f32_e32 v67, v149, v49
	v_fmac_f32_e32 v66, v150, v50
	v_fmac_f32_e32 v67, v151, v51
	ds_read_b128 v[148:151], v105 offset:49296
	s_waitcnt lgkmcnt(11)
	v_fmac_f32_e32 v66, v152, v52
	v_fmac_f32_e32 v67, v153, v53
	v_fmac_f32_e32 v66, v154, v54
	v_fmac_f32_e32 v67, v155, v55
	ds_read_b128 v[152:155], v105 offset:49312
	s_waitcnt lgkmcnt(11)
	v_fmac_f32_e32 v66, v156, v56
	v_sub_f32_e32 v57, v57, v66
	v_sub_f32_e32 v57, v57, v67
	ds_read_b128 v[156:159], v105 offset:49328
	s_waitcnt lgkmcnt(11)
	v_mul_f32_e32 v66, v160, v0
	v_mul_f32_e32 v67, v161, v4
	v_fmac_f32_e32 v66, v162, v5
	v_fmac_f32_e32 v67, v163, v6
	ds_read_b128 v[160:163], v105 offset:49344
	s_waitcnt lgkmcnt(11)
	v_fmac_f32_e32 v66, v164, v7
	v_fmac_f32_e32 v67, v165, v8
	v_fmac_f32_e32 v66, v166, v9
	v_fmac_f32_e32 v67, v167, v10
	ds_read_b128 v[164:167], v105 offset:49360
	s_waitcnt lgkmcnt(11)
	v_fmac_f32_e32 v66, v168, v11
	v_fmac_f32_e32 v67, v169, v12
	v_fmac_f32_e32 v66, v170, v13
	v_fmac_f32_e32 v67, v171, v14
	ds_read_b128 v[168:171], v105 offset:49408
	s_waitcnt lgkmcnt(11)
	v_fmac_f32_e32 v66, v172, v15
	v_fmac_f32_e32 v67, v173, v16
	v_fmac_f32_e32 v66, v174, v17
	v_fmac_f32_e32 v67, v175, v18
	ds_read_b128 v[172:175], v105 offset:49424
	s_waitcnt lgkmcnt(11)
	v_fmac_f32_e32 v66, v176, v20
	v_fmac_f32_e32 v67, v177, v21
	v_fmac_f32_e32 v66, v178, v22
	v_fmac_f32_e32 v67, v179, v23
	ds_read_b128 v[176:179], v105 offset:49440
	s_waitcnt lgkmcnt(11)
	v_fmac_f32_e32 v66, v180, v24
	v_fmac_f32_e32 v67, v181, v25
	v_fmac_f32_e32 v66, v182, v26
	v_fmac_f32_e32 v67, v183, v27
	ds_read_b128 v[180:183], v105 offset:49456
	s_waitcnt lgkmcnt(11)
	v_fmac_f32_e32 v66, v136, v28
	v_fmac_f32_e32 v67, v137, v29
	v_fmac_f32_e32 v66, v138, v30
	v_fmac_f32_e32 v67, v139, v31
	ds_read_b128 v[136:139], v105 offset:49472
	s_waitcnt lgkmcnt(11)
	v_fmac_f32_e32 v66, v140, v32
	v_fmac_f32_e32 v67, v141, v33
	v_fmac_f32_e32 v66, v142, v34
	v_fmac_f32_e32 v67, v143, v35
	ds_read_b128 v[140:143], v105 offset:49488
	s_waitcnt lgkmcnt(11)
	v_fmac_f32_e32 v66, v144, v36
	v_fmac_f32_e32 v67, v145, v37
	v_fmac_f32_e32 v66, v146, v38
	v_fmac_f32_e32 v67, v147, v39
	ds_read_b128 v[144:147], v105 offset:49504
	s_waitcnt lgkmcnt(11)
	v_fmac_f32_e32 v66, v148, v40
	v_fmac_f32_e32 v67, v149, v41
	v_fmac_f32_e32 v66, v150, v42
	v_fmac_f32_e32 v67, v151, v43
	ds_read_b128 v[148:151], v105 offset:49520
	s_waitcnt lgkmcnt(11)
	v_fmac_f32_e32 v66, v152, v44
	v_fmac_f32_e32 v67, v153, v45
	v_fmac_f32_e32 v66, v154, v46
	v_fmac_f32_e32 v67, v155, v47
	ds_read_b128 v[152:155], v105 offset:49536
	s_waitcnt lgkmcnt(11)
	v_fmac_f32_e32 v66, v156, v48
	v_fmac_f32_e32 v67, v157, v49
	v_fmac_f32_e32 v66, v158, v50
	v_fmac_f32_e32 v67, v159, v51
	ds_read_b128 v[156:159], v105 offset:49552
	s_waitcnt lgkmcnt(11)
	v_fmac_f32_e32 v66, v160, v52
	v_fmac_f32_e32 v67, v161, v53
	v_fmac_f32_e32 v66, v162, v54
	v_fmac_f32_e32 v67, v163, v55
	ds_read_b128 v[160:163], v105 offset:49568
	s_waitcnt lgkmcnt(11)
	v_fmac_f32_e32 v66, v164, v56
	v_fmac_f32_e32 v67, v165, v57
	v_sub_f32_e32 v58, v58, v66
	v_sub_f32_e32 v58, v58, v67
	ds_read_b128 v[164:167], v105 offset:49584
	s_waitcnt lgkmcnt(11)
	v_mul_f32_e32 v66, v168, v0
	v_mul_f32_e32 v67, v169, v4
	v_fmac_f32_e32 v66, v170, v5
	v_fmac_f32_e32 v67, v171, v6
	ds_read_b128 v[168:171], v105 offset:49600
	s_waitcnt lgkmcnt(11)
	v_fmac_f32_e32 v66, v172, v7
	v_fmac_f32_e32 v67, v173, v8
	v_fmac_f32_e32 v66, v174, v9
	v_fmac_f32_e32 v67, v175, v10
	ds_read_b128 v[172:175], v105 offset:49616
	s_waitcnt lgkmcnt(11)
	v_fmac_f32_e32 v66, v176, v11
	v_fmac_f32_e32 v67, v177, v12
	v_fmac_f32_e32 v66, v178, v13
	v_fmac_f32_e32 v67, v179, v14
	ds_read_b128 v[176:179], v105 offset:49664
	s_waitcnt lgkmcnt(11)
	v_fmac_f32_e32 v66, v180, v15
	v_fmac_f32_e32 v67, v181, v16
	v_fmac_f32_e32 v66, v182, v17
	v_fmac_f32_e32 v67, v183, v18
	ds_read_b128 v[180:183], v105 offset:49680
	s_waitcnt lgkmcnt(11)
	v_fmac_f32_e32 v66, v136, v20
	v_fmac_f32_e32 v67, v137, v21
	v_fmac_f32_e32 v66, v138, v22
	v_fmac_f32_e32 v67, v139, v23
	ds_read_b128 v[136:139], v105 offset:49696
	s_waitcnt lgkmcnt(11)
	v_fmac_f32_e32 v66, v140, v24
	v_fmac_f32_e32 v67, v141, v25
	v_fmac_f32_e32 v66, v142, v26
	v_fmac_f32_e32 v67, v143, v27
	ds_read_b128 v[140:143], v105 offset:49712
	s_waitcnt lgkmcnt(11)
	v_fmac_f32_e32 v66, v144, v28
	v_fmac_f32_e32 v67, v145, v29
	v_fmac_f32_e32 v66, v146, v30
	v_fmac_f32_e32 v67, v147, v31
	ds_read_b128 v[144:147], v105 offset:49728
	s_waitcnt lgkmcnt(11)
	v_fmac_f32_e32 v66, v148, v32
	v_fmac_f32_e32 v67, v149, v33
	v_fmac_f32_e32 v66, v150, v34
	v_fmac_f32_e32 v67, v151, v35
	ds_read_b128 v[148:151], v105 offset:49744
	s_waitcnt lgkmcnt(11)
	v_fmac_f32_e32 v66, v152, v36
	v_fmac_f32_e32 v67, v153, v37
	v_fmac_f32_e32 v66, v154, v38
	v_fmac_f32_e32 v67, v155, v39
	ds_read_b128 v[152:155], v105 offset:49760
	s_waitcnt lgkmcnt(11)
	v_fmac_f32_e32 v66, v156, v40
	v_fmac_f32_e32 v67, v157, v41
	v_fmac_f32_e32 v66, v158, v42
	v_fmac_f32_e32 v67, v159, v43
	ds_read_b128 v[156:159], v105 offset:49776
	s_waitcnt lgkmcnt(11)
	v_fmac_f32_e32 v66, v160, v44
	v_fmac_f32_e32 v67, v161, v45
	v_fmac_f32_e32 v66, v162, v46
	v_fmac_f32_e32 v67, v163, v47
	ds_read_b128 v[160:163], v105 offset:49792
	s_waitcnt lgkmcnt(11)
	v_fmac_f32_e32 v66, v164, v48
	v_fmac_f32_e32 v67, v165, v49
	v_fmac_f32_e32 v66, v166, v50
	v_fmac_f32_e32 v67, v167, v51
	ds_read_b128 v[164:167], v105 offset:49808
	s_waitcnt lgkmcnt(11)
	v_fmac_f32_e32 v66, v168, v52
	v_fmac_f32_e32 v67, v169, v53
	v_fmac_f32_e32 v66, v170, v54
	v_fmac_f32_e32 v67, v171, v55
	ds_read_b128 v[168:171], v105 offset:49824
	s_waitcnt lgkmcnt(11)
	v_fmac_f32_e32 v66, v172, v56
	v_fmac_f32_e32 v67, v173, v57
	v_fmac_f32_e32 v66, v174, v58
	v_sub_f32_e32 v59, v59, v66
	v_sub_f32_e32 v59, v59, v67
	ds_read_b128 v[172:175], v105 offset:49840
	s_waitcnt lgkmcnt(11)
	v_mul_f32_e32 v66, v176, v0
	v_mul_f32_e32 v67, v177, v4
	v_fmac_f32_e32 v66, v178, v5
	v_fmac_f32_e32 v67, v179, v6
	ds_read_b128 v[176:179], v105 offset:49856
	s_waitcnt lgkmcnt(11)
	v_fmac_f32_e32 v66, v180, v7
	v_fmac_f32_e32 v67, v181, v8
	v_fmac_f32_e32 v66, v182, v9
	v_fmac_f32_e32 v67, v183, v10
	ds_read_b128 v[180:183], v105 offset:49872
	s_waitcnt lgkmcnt(11)
	v_fmac_f32_e32 v66, v136, v11
	v_fmac_f32_e32 v67, v137, v12
	v_fmac_f32_e32 v66, v138, v13
	v_fmac_f32_e32 v67, v139, v14
	ds_read_b128 v[136:139], v105 offset:49920
	s_waitcnt lgkmcnt(11)
	v_fmac_f32_e32 v66, v140, v15
	v_fmac_f32_e32 v67, v141, v16
	v_fmac_f32_e32 v66, v142, v17
	v_fmac_f32_e32 v67, v143, v18
	ds_read_b128 v[140:143], v105 offset:49936
	s_waitcnt lgkmcnt(11)
	v_fmac_f32_e32 v66, v144, v20
	v_fmac_f32_e32 v67, v145, v21
	v_fmac_f32_e32 v66, v146, v22
	v_fmac_f32_e32 v67, v147, v23
	ds_read_b128 v[144:147], v105 offset:49952
	s_waitcnt lgkmcnt(11)
	v_fmac_f32_e32 v66, v148, v24
	v_fmac_f32_e32 v67, v149, v25
	v_fmac_f32_e32 v66, v150, v26
	v_fmac_f32_e32 v67, v151, v27
	ds_read_b128 v[148:151], v105 offset:49968
	s_waitcnt lgkmcnt(11)
	v_fmac_f32_e32 v66, v152, v28
	v_fmac_f32_e32 v67, v153, v29
	v_fmac_f32_e32 v66, v154, v30
	v_fmac_f32_e32 v67, v155, v31
	ds_read_b128 v[152:155], v105 offset:49984
	s_waitcnt lgkmcnt(11)
	v_fmac_f32_e32 v66, v156, v32
	v_fmac_f32_e32 v67, v157, v33
	v_fmac_f32_e32 v66, v158, v34
	v_fmac_f32_e32 v67, v159, v35
	ds_read_b128 v[156:159], v105 offset:50000
	s_waitcnt lgkmcnt(11)
	v_fmac_f32_e32 v66, v160, v36
	v_fmac_f32_e32 v67, v161, v37
	v_fmac_f32_e32 v66, v162, v38
	v_fmac_f32_e32 v67, v163, v39
	ds_read_b128 v[160:163], v105 offset:50016
	s_waitcnt lgkmcnt(11)
	v_fmac_f32_e32 v66, v164, v40
	v_fmac_f32_e32 v67, v165, v41
	v_fmac_f32_e32 v66, v166, v42
	v_fmac_f32_e32 v67, v167, v43
	ds_read_b128 v[164:167], v105 offset:50032
	s_waitcnt lgkmcnt(11)
	v_fmac_f32_e32 v66, v168, v44
	v_fmac_f32_e32 v67, v169, v45
	v_fmac_f32_e32 v66, v170, v46
	v_fmac_f32_e32 v67, v171, v47
	ds_read_b128 v[168:171], v105 offset:50048
	s_waitcnt lgkmcnt(11)
	v_fmac_f32_e32 v66, v172, v48
	v_fmac_f32_e32 v67, v173, v49
	v_fmac_f32_e32 v66, v174, v50
	v_fmac_f32_e32 v67, v175, v51
	ds_read_b128 v[172:175], v105 offset:50064
	s_waitcnt lgkmcnt(11)
	v_fmac_f32_e32 v66, v176, v52
	v_fmac_f32_e32 v67, v177, v53
	v_fmac_f32_e32 v66, v178, v54
	v_fmac_f32_e32 v67, v179, v55
	ds_read_b128 v[176:179], v105 offset:50080
	s_waitcnt lgkmcnt(11)
	v_fmac_f32_e32 v66, v180, v56
	v_fmac_f32_e32 v67, v181, v57
	v_fmac_f32_e32 v66, v182, v58
	v_fmac_f32_e32 v67, v183, v59
	v_sub_f32_e32 v60, v60, v66
	v_sub_f32_e32 v60, v60, v67
	ds_read_b128 v[180:183], v105 offset:50096
	s_waitcnt lgkmcnt(11)
	v_mul_f32_e32 v66, v136, v0
	v_mul_f32_e32 v67, v137, v4
	v_fmac_f32_e32 v66, v138, v5
	v_fmac_f32_e32 v67, v139, v6
	ds_read_b128 v[136:139], v105 offset:50112
	s_waitcnt lgkmcnt(11)
	v_fmac_f32_e32 v66, v140, v7
	v_fmac_f32_e32 v67, v141, v8
	v_fmac_f32_e32 v66, v142, v9
	v_fmac_f32_e32 v67, v143, v10
	ds_read_b128 v[140:143], v105 offset:50128
	s_waitcnt lgkmcnt(11)
	v_fmac_f32_e32 v66, v144, v11
	v_fmac_f32_e32 v67, v145, v12
	v_fmac_f32_e32 v66, v146, v13
	v_fmac_f32_e32 v67, v147, v14
	ds_read_b128 v[144:147], v105 offset:50144
	s_waitcnt lgkmcnt(11)
	v_fmac_f32_e32 v66, v148, v15
	v_fmac_f32_e32 v67, v149, v16
	v_fmac_f32_e32 v66, v150, v17
	v_fmac_f32_e32 v67, v151, v18
	ds_read_b128 v[148:151], v105 offset:50176
	s_waitcnt lgkmcnt(11)
	v_fmac_f32_e32 v66, v152, v20
	v_fmac_f32_e32 v67, v153, v21
	v_fmac_f32_e32 v66, v154, v22
	v_fmac_f32_e32 v67, v155, v23
	ds_read_b128 v[152:155], v105 offset:50192
	s_waitcnt lgkmcnt(11)
	v_fmac_f32_e32 v66, v156, v24
	v_fmac_f32_e32 v67, v157, v25
	v_fmac_f32_e32 v66, v158, v26
	v_fmac_f32_e32 v67, v159, v27
	ds_read_b128 v[156:159], v105 offset:50208
	s_waitcnt lgkmcnt(11)
	v_fmac_f32_e32 v66, v160, v28
	v_fmac_f32_e32 v67, v161, v29
	v_fmac_f32_e32 v66, v162, v30
	v_fmac_f32_e32 v67, v163, v31
	ds_read_b128 v[160:163], v105 offset:50224
	s_waitcnt lgkmcnt(11)
	v_fmac_f32_e32 v66, v164, v32
	v_fmac_f32_e32 v67, v165, v33
	v_fmac_f32_e32 v66, v166, v34
	v_fmac_f32_e32 v67, v167, v35
	ds_read_b128 v[164:167], v105 offset:50240
	s_waitcnt lgkmcnt(11)
	v_fmac_f32_e32 v66, v168, v36
	v_fmac_f32_e32 v67, v169, v37
	v_fmac_f32_e32 v66, v170, v38
	v_fmac_f32_e32 v67, v171, v39
	ds_read_b128 v[168:171], v105 offset:50256
	s_waitcnt lgkmcnt(11)
	v_fmac_f32_e32 v66, v172, v40
	v_fmac_f32_e32 v67, v173, v41
	v_fmac_f32_e32 v66, v174, v42
	v_fmac_f32_e32 v67, v175, v43
	ds_read_b128 v[172:175], v105 offset:50272
	s_waitcnt lgkmcnt(11)
	v_fmac_f32_e32 v66, v176, v44
	v_fmac_f32_e32 v67, v177, v45
	v_fmac_f32_e32 v66, v178, v46
	v_fmac_f32_e32 v67, v179, v47
	ds_read_b128 v[176:179], v105 offset:50288
	s_waitcnt lgkmcnt(11)
	v_fmac_f32_e32 v66, v180, v48
	v_fmac_f32_e32 v67, v181, v49
	v_fmac_f32_e32 v66, v182, v50
	v_fmac_f32_e32 v67, v183, v51
	ds_read_b128 v[180:183], v105 offset:50304
	s_waitcnt lgkmcnt(11)
	v_fmac_f32_e32 v66, v136, v52
	v_fmac_f32_e32 v67, v137, v53
	v_fmac_f32_e32 v66, v138, v54
	v_fmac_f32_e32 v67, v139, v55
	ds_read_b128 v[136:139], v105 offset:50320
	s_waitcnt lgkmcnt(11)
	v_fmac_f32_e32 v66, v140, v56
	v_fmac_f32_e32 v67, v141, v57
	v_fmac_f32_e32 v66, v142, v58
	v_fmac_f32_e32 v67, v143, v59
	ds_read_b128 v[140:143], v105 offset:50336
	s_waitcnt lgkmcnt(11)
	v_fmac_f32_e32 v66, v144, v60
	v_sub_f32_e32 v61, v61, v66
	v_sub_f32_e32 v61, v61, v67
	ds_read_b128 v[144:147], v105 offset:50352
	s_waitcnt lgkmcnt(11)
	v_mul_f32_e32 v66, v148, v0
	v_mul_f32_e32 v67, v149, v4
	v_fmac_f32_e32 v66, v150, v5
	v_fmac_f32_e32 v67, v151, v6
	ds_read_b128 v[148:151], v105 offset:50368
	s_waitcnt lgkmcnt(11)
	v_fmac_f32_e32 v66, v152, v7
	v_fmac_f32_e32 v67, v153, v8
	v_fmac_f32_e32 v66, v154, v9
	v_fmac_f32_e32 v67, v155, v10
	ds_read_b128 v[152:155], v105 offset:50384
	s_waitcnt lgkmcnt(11)
	v_fmac_f32_e32 v66, v156, v11
	v_fmac_f32_e32 v67, v157, v12
	v_fmac_f32_e32 v66, v158, v13
	v_fmac_f32_e32 v67, v159, v14
	ds_read_b128 v[156:159], v105 offset:50400
	s_waitcnt lgkmcnt(11)
	v_fmac_f32_e32 v66, v160, v15
	v_fmac_f32_e32 v67, v161, v16
	v_fmac_f32_e32 v66, v162, v17
	v_fmac_f32_e32 v67, v163, v18
	ds_read_b128 v[160:163], v105 offset:50432
	s_waitcnt lgkmcnt(11)
	v_fmac_f32_e32 v66, v164, v20
	v_fmac_f32_e32 v67, v165, v21
	v_fmac_f32_e32 v66, v166, v22
	v_fmac_f32_e32 v67, v167, v23
	ds_read_b128 v[164:167], v105 offset:50448
	s_waitcnt lgkmcnt(11)
	v_fmac_f32_e32 v66, v168, v24
	v_fmac_f32_e32 v67, v169, v25
	v_fmac_f32_e32 v66, v170, v26
	v_fmac_f32_e32 v67, v171, v27
	ds_read_b128 v[168:171], v105 offset:50464
	s_waitcnt lgkmcnt(11)
	v_fmac_f32_e32 v66, v172, v28
	v_fmac_f32_e32 v67, v173, v29
	v_fmac_f32_e32 v66, v174, v30
	v_fmac_f32_e32 v67, v175, v31
	ds_read_b128 v[172:175], v105 offset:50480
	s_waitcnt lgkmcnt(11)
	v_fmac_f32_e32 v66, v176, v32
	v_fmac_f32_e32 v67, v177, v33
	v_fmac_f32_e32 v66, v178, v34
	v_fmac_f32_e32 v67, v179, v35
	ds_read_b128 v[176:179], v105 offset:50496
	s_waitcnt lgkmcnt(11)
	v_fmac_f32_e32 v66, v180, v36
	v_fmac_f32_e32 v67, v181, v37
	v_fmac_f32_e32 v66, v182, v38
	v_fmac_f32_e32 v67, v183, v39
	ds_read_b128 v[180:183], v105 offset:50512
	s_waitcnt lgkmcnt(11)
	v_fmac_f32_e32 v66, v136, v40
	v_fmac_f32_e32 v67, v137, v41
	v_fmac_f32_e32 v66, v138, v42
	v_fmac_f32_e32 v67, v139, v43
	ds_read_b128 v[136:139], v105 offset:50528
	s_waitcnt lgkmcnt(11)
	v_fmac_f32_e32 v66, v140, v44
	v_fmac_f32_e32 v67, v141, v45
	v_fmac_f32_e32 v66, v142, v46
	v_fmac_f32_e32 v67, v143, v47
	ds_read_b128 v[140:143], v105 offset:50544
	s_waitcnt lgkmcnt(11)
	v_fmac_f32_e32 v66, v144, v48
	v_fmac_f32_e32 v67, v145, v49
	v_fmac_f32_e32 v66, v146, v50
	v_fmac_f32_e32 v67, v147, v51
	ds_read_b128 v[144:147], v105 offset:50560
	s_waitcnt lgkmcnt(11)
	v_fmac_f32_e32 v66, v148, v52
	v_fmac_f32_e32 v67, v149, v53
	v_fmac_f32_e32 v66, v150, v54
	v_fmac_f32_e32 v67, v151, v55
	ds_read_b128 v[148:151], v105 offset:50576
	s_waitcnt lgkmcnt(11)
	v_fmac_f32_e32 v66, v152, v56
	v_fmac_f32_e32 v67, v153, v57
	v_fmac_f32_e32 v66, v154, v58
	v_fmac_f32_e32 v67, v155, v59
	ds_read_b128 v[152:155], v105 offset:50592
	s_waitcnt lgkmcnt(11)
	v_fmac_f32_e32 v66, v156, v60
	v_fmac_f32_e32 v67, v157, v61
	v_sub_f32_e32 v62, v62, v66
	v_sub_f32_e32 v62, v62, v67
	ds_read_b128 v[156:159], v105 offset:50608
	s_waitcnt lgkmcnt(11)
	v_mul_f32_e32 v66, v160, v0
	v_mul_f32_e32 v67, v161, v4
	v_fmac_f32_e32 v66, v162, v5
	v_fmac_f32_e32 v67, v163, v6
	ds_read_b128 v[160:163], v105 offset:50624
	s_waitcnt lgkmcnt(11)
	v_fmac_f32_e32 v66, v164, v7
	v_fmac_f32_e32 v67, v165, v8
	v_fmac_f32_e32 v66, v166, v9
	v_fmac_f32_e32 v67, v167, v10
	ds_read_b128 v[164:167], v105 offset:50640
	s_waitcnt lgkmcnt(11)
	v_fmac_f32_e32 v66, v168, v11
	v_fmac_f32_e32 v67, v169, v12
	v_fmac_f32_e32 v66, v170, v13
	v_fmac_f32_e32 v67, v171, v14
	ds_read_b128 v[168:171], v105 offset:50656
	s_waitcnt lgkmcnt(11)
	v_fmac_f32_e32 v66, v172, v15
	v_fmac_f32_e32 v67, v173, v16
	v_fmac_f32_e32 v66, v174, v17
	v_fmac_f32_e32 v67, v175, v18
	ds_read_b128 v[172:175], v105 offset:50688
	s_waitcnt lgkmcnt(11)
	v_fmac_f32_e32 v66, v176, v20
	v_fmac_f32_e32 v67, v177, v21
	v_fmac_f32_e32 v66, v178, v22
	v_fmac_f32_e32 v67, v179, v23
	ds_read_b128 v[176:179], v105 offset:50704
	s_waitcnt lgkmcnt(11)
	v_fmac_f32_e32 v66, v180, v24
	v_fmac_f32_e32 v67, v181, v25
	v_fmac_f32_e32 v66, v182, v26
	v_fmac_f32_e32 v67, v183, v27
	ds_read_b128 v[180:183], v105 offset:50720
	s_waitcnt lgkmcnt(11)
	v_fmac_f32_e32 v66, v136, v28
	v_fmac_f32_e32 v67, v137, v29
	v_fmac_f32_e32 v66, v138, v30
	v_fmac_f32_e32 v67, v139, v31
	ds_read_b128 v[136:139], v105 offset:50736
	s_waitcnt lgkmcnt(11)
	v_fmac_f32_e32 v66, v140, v32
	v_fmac_f32_e32 v67, v141, v33
	v_fmac_f32_e32 v66, v142, v34
	v_fmac_f32_e32 v67, v143, v35
	ds_read_b128 v[140:143], v105 offset:50752
	s_waitcnt lgkmcnt(11)
	v_fmac_f32_e32 v66, v144, v36
	v_fmac_f32_e32 v67, v145, v37
	v_fmac_f32_e32 v66, v146, v38
	v_fmac_f32_e32 v67, v147, v39
	ds_read_b128 v[144:147], v105 offset:50768
	s_waitcnt lgkmcnt(11)
	v_fmac_f32_e32 v66, v148, v40
	v_fmac_f32_e32 v67, v149, v41
	v_fmac_f32_e32 v66, v150, v42
	v_fmac_f32_e32 v67, v151, v43
	ds_read_b128 v[148:151], v105 offset:50784
	s_waitcnt lgkmcnt(11)
	v_fmac_f32_e32 v66, v152, v44
	v_fmac_f32_e32 v67, v153, v45
	v_fmac_f32_e32 v66, v154, v46
	v_fmac_f32_e32 v67, v155, v47
	ds_read_b128 v[152:155], v105 offset:50800
	s_waitcnt lgkmcnt(11)
	v_fmac_f32_e32 v66, v156, v48
	v_fmac_f32_e32 v67, v157, v49
	v_fmac_f32_e32 v66, v158, v50
	v_fmac_f32_e32 v67, v159, v51
	ds_read_b128 v[156:159], v105 offset:50816
	s_waitcnt lgkmcnt(11)
	v_fmac_f32_e32 v66, v160, v52
	v_fmac_f32_e32 v67, v161, v53
	v_fmac_f32_e32 v66, v162, v54
	v_fmac_f32_e32 v67, v163, v55
	ds_read_b128 v[160:163], v105 offset:50832
	s_waitcnt lgkmcnt(11)
	v_fmac_f32_e32 v66, v164, v56
	v_fmac_f32_e32 v67, v165, v57
	v_fmac_f32_e32 v66, v166, v58
	v_fmac_f32_e32 v67, v167, v59
	ds_read_b128 v[164:167], v105 offset:50848
	s_waitcnt lgkmcnt(11)
	v_fmac_f32_e32 v66, v168, v60
	v_fmac_f32_e32 v67, v169, v61
	v_fmac_f32_e32 v66, v170, v62
	v_sub_f32_e32 v63, v63, v66
	v_sub_f32_e32 v63, v63, v67
	ds_read_b128 v[168:171], v105 offset:50864
	s_waitcnt lgkmcnt(11)
	v_mul_f32_e32 v66, v172, v0
	v_mul_f32_e32 v67, v173, v4
	v_fmac_f32_e32 v66, v174, v5
	v_fmac_f32_e32 v67, v175, v6
	ds_read_b128 v[172:175], v105 offset:50880
	s_waitcnt lgkmcnt(11)
	v_fmac_f32_e32 v66, v176, v7
	v_fmac_f32_e32 v67, v177, v8
	v_fmac_f32_e32 v66, v178, v9
	v_fmac_f32_e32 v67, v179, v10
	ds_read_b128 v[176:179], v105 offset:50896
	s_waitcnt lgkmcnt(11)
	v_fmac_f32_e32 v66, v180, v11
	v_fmac_f32_e32 v67, v181, v12
	v_fmac_f32_e32 v66, v182, v13
	v_fmac_f32_e32 v67, v183, v14
	ds_read_b128 v[180:183], v105 offset:50912
	s_waitcnt lgkmcnt(11)
	v_fmac_f32_e32 v66, v136, v15
	v_fmac_f32_e32 v67, v137, v16
	v_fmac_f32_e32 v66, v138, v17
	v_fmac_f32_e32 v67, v139, v18
	ds_read_b128 v[136:139], v105 offset:50944
	s_waitcnt lgkmcnt(11)
	v_fmac_f32_e32 v66, v140, v20
	v_fmac_f32_e32 v67, v141, v21
	v_fmac_f32_e32 v66, v142, v22
	v_fmac_f32_e32 v67, v143, v23
	ds_read_b128 v[140:143], v105 offset:50960
	s_waitcnt lgkmcnt(11)
	v_fmac_f32_e32 v66, v144, v24
	v_fmac_f32_e32 v67, v145, v25
	v_fmac_f32_e32 v66, v146, v26
	v_fmac_f32_e32 v67, v147, v27
	ds_read_b128 v[144:147], v105 offset:50976
	s_waitcnt lgkmcnt(11)
	v_fmac_f32_e32 v66, v148, v28
	v_fmac_f32_e32 v67, v149, v29
	v_fmac_f32_e32 v66, v150, v30
	v_fmac_f32_e32 v67, v151, v31
	ds_read_b128 v[148:151], v105 offset:50992
	s_waitcnt lgkmcnt(11)
	v_fmac_f32_e32 v66, v152, v32
	v_fmac_f32_e32 v67, v153, v33
	v_fmac_f32_e32 v66, v154, v34
	v_fmac_f32_e32 v67, v155, v35
	ds_read_b128 v[152:155], v105 offset:51008
	s_waitcnt lgkmcnt(11)
	v_fmac_f32_e32 v66, v156, v36
	v_fmac_f32_e32 v67, v157, v37
	v_fmac_f32_e32 v66, v158, v38
	v_fmac_f32_e32 v67, v159, v39
	ds_read_b128 v[156:159], v105 offset:51024
	s_waitcnt lgkmcnt(11)
	v_fmac_f32_e32 v66, v160, v40
	v_fmac_f32_e32 v67, v161, v41
	v_fmac_f32_e32 v66, v162, v42
	v_fmac_f32_e32 v67, v163, v43
	ds_read_b128 v[160:163], v105 offset:51040
	s_waitcnt lgkmcnt(11)
	v_fmac_f32_e32 v66, v164, v44
	v_fmac_f32_e32 v67, v165, v45
	v_fmac_f32_e32 v66, v166, v46
	v_fmac_f32_e32 v67, v167, v47
	ds_read_b128 v[164:167], v105 offset:51056
	s_waitcnt lgkmcnt(11)
	v_fmac_f32_e32 v66, v168, v48
	v_fmac_f32_e32 v67, v169, v49
	v_fmac_f32_e32 v66, v170, v50
	v_fmac_f32_e32 v67, v171, v51
	ds_read_b128 v[168:171], v105 offset:51072
	s_waitcnt lgkmcnt(11)
	v_fmac_f32_e32 v66, v172, v52
	v_fmac_f32_e32 v67, v173, v53
	v_fmac_f32_e32 v66, v174, v54
	v_fmac_f32_e32 v67, v175, v55
	ds_read_b128 v[172:175], v105 offset:51088
	s_waitcnt lgkmcnt(11)
	v_fmac_f32_e32 v66, v176, v56
	v_fmac_f32_e32 v67, v177, v57
	v_fmac_f32_e32 v66, v178, v58
	v_fmac_f32_e32 v67, v179, v59
	ds_read_b128 v[176:179], v105 offset:51104
	s_waitcnt lgkmcnt(11)
	v_fmac_f32_e32 v66, v180, v60
	v_fmac_f32_e32 v67, v181, v61
	v_fmac_f32_e32 v66, v182, v62
	v_fmac_f32_e32 v67, v183, v63
	v_sub_f32_e32 v64, v64, v66
	v_sub_f32_e32 v64, v64, v67
	ds_read_b128 v[180:183], v105 offset:51120
	s_waitcnt lgkmcnt(11)
	v_mul_f32_e32 v66, v136, v0
	v_mul_f32_e32 v67, v137, v4
	v_fmac_f32_e32 v66, v138, v5
	v_fmac_f32_e32 v67, v139, v6
	ds_read_b128 v[136:139], v105 offset:51136
	s_waitcnt lgkmcnt(11)
	v_fmac_f32_e32 v66, v140, v7
	v_fmac_f32_e32 v67, v141, v8
	v_fmac_f32_e32 v66, v142, v9
	v_fmac_f32_e32 v67, v143, v10
	ds_read_b128 v[140:143], v105 offset:51152
	s_waitcnt lgkmcnt(11)
	v_fmac_f32_e32 v66, v144, v11
	v_fmac_f32_e32 v67, v145, v12
	v_fmac_f32_e32 v66, v146, v13
	v_fmac_f32_e32 v67, v147, v14
	ds_read_b128 v[144:147], v105 offset:51168
	s_waitcnt lgkmcnt(11)
	v_fmac_f32_e32 v66, v148, v15
	v_fmac_f32_e32 v67, v149, v16
	v_fmac_f32_e32 v66, v150, v17
	v_fmac_f32_e32 v67, v151, v18
	ds_read_b128 v[148:151], v105 offset:51184
	s_waitcnt lgkmcnt(11)
	v_fmac_f32_e32 v66, v152, v20
	v_fmac_f32_e32 v67, v153, v21
	v_fmac_f32_e32 v66, v154, v22
	v_fmac_f32_e32 v67, v155, v23
	ds_read_b128 v[152:155], v105 offset:51200
	s_waitcnt lgkmcnt(11)
	v_fmac_f32_e32 v66, v156, v24
	v_fmac_f32_e32 v67, v157, v25
	v_fmac_f32_e32 v66, v158, v26
	v_fmac_f32_e32 v67, v159, v27
	ds_read_b128 v[156:159], v105 offset:51216
	s_waitcnt lgkmcnt(11)
	v_fmac_f32_e32 v66, v160, v28
	v_fmac_f32_e32 v67, v161, v29
	v_fmac_f32_e32 v66, v162, v30
	v_fmac_f32_e32 v67, v163, v31
	ds_read_b128 v[160:163], v105 offset:51232
	s_waitcnt lgkmcnt(11)
	v_fmac_f32_e32 v66, v164, v32
	v_fmac_f32_e32 v67, v165, v33
	v_fmac_f32_e32 v66, v166, v34
	v_fmac_f32_e32 v67, v167, v35
	ds_read_b128 v[164:167], v105 offset:51248
	s_waitcnt lgkmcnt(11)
	v_fmac_f32_e32 v66, v168, v36
	v_fmac_f32_e32 v67, v169, v37
	v_fmac_f32_e32 v66, v170, v38
	v_fmac_f32_e32 v67, v171, v39
	ds_read_b128 v[168:171], v105 offset:51264
	s_waitcnt lgkmcnt(11)
	v_fmac_f32_e32 v66, v172, v40
	v_fmac_f32_e32 v67, v173, v41
	v_fmac_f32_e32 v66, v174, v42
	v_fmac_f32_e32 v67, v175, v43
	ds_read_b128 v[172:175], v105 offset:51280
	s_waitcnt lgkmcnt(11)
	v_fmac_f32_e32 v66, v176, v44
	v_fmac_f32_e32 v67, v177, v45
	v_fmac_f32_e32 v66, v178, v46
	v_fmac_f32_e32 v67, v179, v47
	ds_read_b128 v[176:179], v105 offset:51296
	s_waitcnt lgkmcnt(11)
	v_fmac_f32_e32 v66, v180, v48
	v_fmac_f32_e32 v67, v181, v49
	v_fmac_f32_e32 v66, v182, v50
	v_fmac_f32_e32 v67, v183, v51
	ds_read_b128 v[180:183], v105 offset:51312
	s_waitcnt lgkmcnt(11)
	v_fmac_f32_e32 v66, v136, v52
	v_fmac_f32_e32 v67, v137, v53
	v_fmac_f32_e32 v66, v138, v54
	v_fmac_f32_e32 v67, v139, v55
	ds_read_b128 v[136:139], v105 offset:51328
	s_waitcnt lgkmcnt(11)
	v_fmac_f32_e32 v66, v140, v56
	v_fmac_f32_e32 v67, v141, v57
	v_fmac_f32_e32 v66, v142, v58
	v_fmac_f32_e32 v67, v143, v59
	ds_read_b128 v[140:143], v105 offset:51344
	s_waitcnt lgkmcnt(11)
	v_fmac_f32_e32 v66, v144, v60
	v_fmac_f32_e32 v67, v145, v61
	v_fmac_f32_e32 v66, v146, v62
	v_fmac_f32_e32 v67, v147, v63
	ds_read_b128 v[144:147], v105 offset:51360
	s_waitcnt lgkmcnt(11)
	v_fmac_f32_e32 v66, v148, v64
	v_sub_f32_e32 v65, v65, v66
	v_sub_f32_e32 v65, v65, v67
	ds_read_b128 v[148:151], v105 offset:51376
	s_waitcnt lgkmcnt(11)
	v_mul_f32_e32 v66, v152, v0
	v_mul_f32_e32 v67, v153, v4
	v_fmac_f32_e32 v66, v154, v5
	v_fmac_f32_e32 v67, v155, v6
	ds_read_b128 v[152:155], v105 offset:51392
	s_waitcnt lgkmcnt(11)
	v_fmac_f32_e32 v66, v156, v7
	v_fmac_f32_e32 v67, v157, v8
	v_fmac_f32_e32 v66, v158, v9
	v_fmac_f32_e32 v67, v159, v10
	ds_read_b128 v[156:159], v105 offset:51408
	s_waitcnt lgkmcnt(11)
	v_fmac_f32_e32 v66, v160, v11
	v_fmac_f32_e32 v67, v161, v12
	v_fmac_f32_e32 v66, v162, v13
	v_fmac_f32_e32 v67, v163, v14
	ds_read_b128 v[160:163], v105 offset:51424
	s_waitcnt lgkmcnt(11)
	v_fmac_f32_e32 v66, v164, v15
	v_fmac_f32_e32 v67, v165, v16
	v_fmac_f32_e32 v66, v166, v17
	v_fmac_f32_e32 v67, v167, v18
	ds_read_b128 v[164:167], v105 offset:51440
	s_waitcnt lgkmcnt(11)
	v_fmac_f32_e32 v66, v168, v20
	v_fmac_f32_e32 v67, v169, v21
	v_fmac_f32_e32 v66, v170, v22
	v_fmac_f32_e32 v67, v171, v23
	ds_read_b128 v[168:171], v105 offset:51456
	s_waitcnt lgkmcnt(11)
	v_fmac_f32_e32 v66, v172, v24
	v_fmac_f32_e32 v67, v173, v25
	v_fmac_f32_e32 v66, v174, v26
	v_fmac_f32_e32 v67, v175, v27
	ds_read_b128 v[172:175], v105 offset:51472
	s_waitcnt lgkmcnt(11)
	v_fmac_f32_e32 v66, v176, v28
	v_fmac_f32_e32 v67, v177, v29
	v_fmac_f32_e32 v66, v178, v30
	v_fmac_f32_e32 v67, v179, v31
	ds_read_b128 v[176:179], v105 offset:51488
	s_waitcnt lgkmcnt(11)
	v_fmac_f32_e32 v66, v180, v32
	v_fmac_f32_e32 v67, v181, v33
	v_fmac_f32_e32 v66, v182, v34
	v_fmac_f32_e32 v67, v183, v35
	ds_read_b128 v[180:183], v105 offset:51504
	s_waitcnt lgkmcnt(11)
	v_fmac_f32_e32 v66, v136, v36
	v_fmac_f32_e32 v67, v137, v37
	v_fmac_f32_e32 v66, v138, v38
	v_fmac_f32_e32 v67, v139, v39
	ds_read_b128 v[136:139], v105 offset:51520
	s_waitcnt lgkmcnt(11)
	v_fmac_f32_e32 v66, v140, v40
	v_fmac_f32_e32 v67, v141, v41
	v_fmac_f32_e32 v66, v142, v42
	v_fmac_f32_e32 v67, v143, v43
	ds_read_b128 v[140:143], v105 offset:51536
	s_waitcnt lgkmcnt(11)
	v_fmac_f32_e32 v66, v144, v44
	v_fmac_f32_e32 v67, v145, v45
	v_fmac_f32_e32 v66, v146, v46
	v_fmac_f32_e32 v67, v147, v47
	ds_read_b128 v[144:147], v105 offset:51552
	s_waitcnt lgkmcnt(11)
	v_fmac_f32_e32 v66, v148, v48
	v_fmac_f32_e32 v67, v149, v49
	v_fmac_f32_e32 v66, v150, v50
	v_fmac_f32_e32 v67, v151, v51
	ds_read_b128 v[148:151], v105 offset:51568
	s_waitcnt lgkmcnt(11)
	v_fmac_f32_e32 v66, v152, v52
	v_fmac_f32_e32 v67, v153, v53
	v_fmac_f32_e32 v66, v154, v54
	v_fmac_f32_e32 v67, v155, v55
	ds_read_b128 v[152:155], v105 offset:51584
	s_waitcnt lgkmcnt(11)
	v_fmac_f32_e32 v66, v156, v56
	v_fmac_f32_e32 v67, v157, v57
	v_fmac_f32_e32 v66, v158, v58
	v_fmac_f32_e32 v67, v159, v59
	ds_read_b128 v[156:159], v105 offset:51600
	s_waitcnt lgkmcnt(11)
	v_fmac_f32_e32 v66, v160, v60
	v_fmac_f32_e32 v67, v161, v61
	v_fmac_f32_e32 v66, v162, v62
	v_fmac_f32_e32 v67, v163, v63
	ds_read_b128 v[160:163], v105 offset:51616
	s_waitcnt lgkmcnt(11)
	v_fmac_f32_e32 v66, v164, v64
	v_fmac_f32_e32 v67, v165, v65
	v_sub_f32_e32 v2, v2, v66
	v_sub_f32_e32 v2, v2, v67
	ds_read_b128 v[164:167], v105 offset:51632
	s_waitcnt lgkmcnt(11)
	v_mul_f32_e32 v66, v168, v0
	v_mul_f32_e32 v67, v169, v4
	v_fmac_f32_e32 v66, v170, v5
	v_fmac_f32_e32 v67, v171, v6
	ds_read_b128 v[168:171], v105 offset:51648
	s_waitcnt lgkmcnt(11)
	v_fmac_f32_e32 v66, v172, v7
	v_fmac_f32_e32 v67, v173, v8
	v_fmac_f32_e32 v66, v174, v9
	v_fmac_f32_e32 v67, v175, v10
	ds_read_b128 v[172:175], v105 offset:51664
	s_waitcnt lgkmcnt(11)
	v_fmac_f32_e32 v66, v176, v11
	v_fmac_f32_e32 v67, v177, v12
	v_fmac_f32_e32 v66, v178, v13
	v_fmac_f32_e32 v67, v179, v14
	ds_read_b128 v[176:179], v105 offset:51680
	s_waitcnt lgkmcnt(11)
	v_fmac_f32_e32 v66, v180, v15
	v_fmac_f32_e32 v67, v181, v16
	v_fmac_f32_e32 v66, v182, v17
	v_fmac_f32_e32 v67, v183, v18
	ds_read_b128 v[180:183], v105 offset:51696
	s_waitcnt lgkmcnt(11)
	v_fmac_f32_e32 v66, v136, v20
	v_fmac_f32_e32 v67, v137, v21
	v_fmac_f32_e32 v66, v138, v22
	v_fmac_f32_e32 v67, v139, v23
	s_waitcnt lgkmcnt(10)
	v_fmac_f32_e32 v66, v140, v24
	v_fmac_f32_e32 v67, v141, v25
	v_fmac_f32_e32 v66, v142, v26
	v_fmac_f32_e32 v67, v143, v27
	s_waitcnt lgkmcnt(9)
	v_fmac_f32_e32 v66, v144, v28
	v_fmac_f32_e32 v67, v145, v29
	v_fmac_f32_e32 v66, v146, v30
	v_fmac_f32_e32 v67, v147, v31
	s_waitcnt lgkmcnt(8)
	v_fmac_f32_e32 v66, v148, v32
	v_fmac_f32_e32 v67, v149, v33
	v_fmac_f32_e32 v66, v150, v34
	v_fmac_f32_e32 v67, v151, v35
	s_waitcnt lgkmcnt(7)
	v_fmac_f32_e32 v66, v152, v36
	v_fmac_f32_e32 v67, v153, v37
	v_fmac_f32_e32 v66, v154, v38
	v_fmac_f32_e32 v67, v155, v39
	s_waitcnt lgkmcnt(6)
	v_fmac_f32_e32 v66, v156, v40
	v_fmac_f32_e32 v67, v157, v41
	v_fmac_f32_e32 v66, v158, v42
	v_fmac_f32_e32 v67, v159, v43
	s_waitcnt lgkmcnt(5)
	v_fmac_f32_e32 v66, v160, v44
	v_fmac_f32_e32 v67, v161, v45
	v_fmac_f32_e32 v66, v162, v46
	v_fmac_f32_e32 v67, v163, v47
	s_waitcnt lgkmcnt(4)
	v_fmac_f32_e32 v66, v164, v48
	v_fmac_f32_e32 v67, v165, v49
	v_fmac_f32_e32 v66, v166, v50
	v_fmac_f32_e32 v67, v167, v51
	s_waitcnt lgkmcnt(3)
	v_fmac_f32_e32 v66, v168, v52
	v_fmac_f32_e32 v67, v169, v53
	v_fmac_f32_e32 v66, v170, v54
	v_fmac_f32_e32 v67, v171, v55
	s_waitcnt lgkmcnt(2)
	v_fmac_f32_e32 v66, v172, v56
	v_fmac_f32_e32 v67, v173, v57
	v_fmac_f32_e32 v66, v174, v58
	v_fmac_f32_e32 v67, v175, v59
	s_waitcnt lgkmcnt(1)
	v_fmac_f32_e32 v66, v176, v60
	v_fmac_f32_e32 v67, v177, v61
	v_fmac_f32_e32 v66, v178, v62
	v_fmac_f32_e32 v67, v179, v63
	s_waitcnt lgkmcnt(0)
	v_fmac_f32_e32 v66, v180, v64
	v_fmac_f32_e32 v67, v181, v65
	v_fmac_f32_e32 v66, v182, v2
	v_sub_f32_e32 v3, v3, v66
	v_sub_f32_e32 v3, v3, v67
	s_movk_i32 s4, 0x7f
	v_cmp_lt_i32_e32 vcc, s4, v80
	s_and_saveexec_b64 s[4:5], vcc
	s_xor_b64 s[36:37], exec, s[4:5]
	s_cbranch_execz .LBB0_936
	v_mov_b32_e32 v81, v105
	v_lshl_add_u64 v[66:67], v[80:81], 1, s[38:39]
	v_cvt_pk_bf16_f32 v0, v0, s0
	global_store_short v[66:67], v0, off offset:-256
	v_cvt_pk_bf16_f32 v0, v4, s0
	global_store_short v[66:67], v0, off
	v_cvt_pk_bf16_f32 v0, v5, s0
	global_store_short v[66:67], v0, off offset:256
	v_cvt_pk_bf16_f32 v0, v6, s0
	global_store_short v[66:67], v0, off offset:512
	v_cvt_pk_bf16_f32 v0, v7, s0
	global_store_short v[66:67], v0, off offset:768
	v_cvt_pk_bf16_f32 v0, v8, s0
	global_store_short v[66:67], v0, off offset:1024
	v_cvt_pk_bf16_f32 v0, v9, s0
	global_store_short v[66:67], v0, off offset:1280
	v_cvt_pk_bf16_f32 v0, v10, s0
	global_store_short v[66:67], v0, off offset:1536
	v_cvt_pk_bf16_f32 v0, v11, s0
	global_store_short v[66:67], v0, off offset:1792
	v_cvt_pk_bf16_f32 v0, v12, s0
	global_store_short v[66:67], v0, off offset:2048
	v_cvt_pk_bf16_f32 v0, v13, s0
	global_store_short v[66:67], v0, off offset:2304
	v_cvt_pk_bf16_f32 v0, v14, s0
	global_store_short v[66:67], v0, off offset:2560
	v_cvt_pk_bf16_f32 v0, v15, s0
	global_store_short v[66:67], v0, off offset:2816
	v_cvt_pk_bf16_f32 v0, v16, s0
	global_store_short v[66:67], v0, off offset:3072
	v_cvt_pk_bf16_f32 v0, v17, s0
	global_store_short v[66:67], v0, off offset:3328
	v_cvt_pk_bf16_f32 v0, v18, s0
	global_store_short v[66:67], v0, off offset:3584
	v_cvt_pk_bf16_f32 v0, v20, s0
	s_movk_i32 s4, 0x1000
	global_store_short v[66:67], v0, off offset:3840
	v_add_co_u32_e32 v0, vcc, s4, v66
	s_movk_i32 s4, 0x2000
	s_nop 0
	v_addc_co_u32_e32 v1, vcc, 0, v67, vcc
	v_add_co_u32_e32 v4, vcc, s4, v66
	v_cvt_pk_bf16_f32 v6, v21, s0
	s_nop 0
	v_addc_co_u32_e32 v5, vcc, 0, v67, vcc
	global_store_short v[4:5], v6, off offset:-4096
	v_cvt_pk_bf16_f32 v6, v22, s0
	global_store_short v[0:1], v6, off offset:256
	v_cvt_pk_bf16_f32 v6, v23, s0
	global_store_short v[0:1], v6, off offset:512
	v_cvt_pk_bf16_f32 v6, v24, s0
	global_store_short v[0:1], v6, off offset:768
	v_cvt_pk_bf16_f32 v6, v25, s0
	global_store_short v[0:1], v6, off offset:1024
	v_cvt_pk_bf16_f32 v6, v26, s0
	global_store_short v[0:1], v6, off offset:1280
	v_cvt_pk_bf16_f32 v6, v27, s0
	global_store_short v[0:1], v6, off offset:1536
	v_cvt_pk_bf16_f32 v6, v28, s0
	global_store_short v[0:1], v6, off offset:1792
	v_cvt_pk_bf16_f32 v6, v29, s0
	global_store_short v[0:1], v6, off offset:2048
	v_cvt_pk_bf16_f32 v6, v30, s0
	global_store_short v[0:1], v6, off offset:2304
	v_cvt_pk_bf16_f32 v6, v31, s0
	global_store_short v[0:1], v6, off offset:2560
	v_cvt_pk_bf16_f32 v6, v32, s0
	global_store_short v[0:1], v6, off offset:2816
	v_cvt_pk_bf16_f32 v6, v33, s0
	global_store_short v[0:1], v6, off offset:3072
	v_cvt_pk_bf16_f32 v6, v34, s0
	global_store_short v[0:1], v6, off offset:3328
	v_cvt_pk_bf16_f32 v6, v35, s0
	global_store_short v[0:1], v6, off offset:3584
	v_cvt_pk_bf16_f32 v6, v36, s0
	global_store_short v[0:1], v6, off offset:3840
	v_cvt_pk_bf16_f32 v0, v37, s0
	global_store_short v[4:5], v0, off
	v_cvt_pk_bf16_f32 v0, v38, s0
	global_store_short v[4:5], v0, off offset:256
	v_cvt_pk_bf16_f32 v0, v39, s0
	global_store_short v[4:5], v0, off offset:512
	v_cvt_pk_bf16_f32 v0, v40, s0
	global_store_short v[4:5], v0, off offset:768
	v_cvt_pk_bf16_f32 v0, v41, s0
	global_store_short v[4:5], v0, off offset:1024
	v_cvt_pk_bf16_f32 v0, v42, s0
	global_store_short v[4:5], v0, off offset:1280
	v_cvt_pk_bf16_f32 v0, v43, s0
	global_store_short v[4:5], v0, off offset:1536
	v_cvt_pk_bf16_f32 v0, v44, s0
	global_store_short v[4:5], v0, off offset:1792
	v_cvt_pk_bf16_f32 v0, v45, s0
	global_store_short v[4:5], v0, off offset:2048
	v_cvt_pk_bf16_f32 v0, v46, s0
	global_store_short v[4:5], v0, off offset:2304
	v_cvt_pk_bf16_f32 v0, v47, s0
	global_store_short v[4:5], v0, off offset:2560
	v_cvt_pk_bf16_f32 v0, v48, s0
	global_store_short v[4:5], v0, off offset:2816
	v_cvt_pk_bf16_f32 v0, v49, s0
	global_store_short v[4:5], v0, off offset:3072
	v_cvt_pk_bf16_f32 v0, v50, s0
	global_store_short v[4:5], v0, off offset:3328
	v_cvt_pk_bf16_f32 v0, v51, s0
	global_store_short v[4:5], v0, off offset:3584
	v_cvt_pk_bf16_f32 v0, v52, s0
	global_store_short v[4:5], v0, off offset:3840
	v_add_co_u32_e32 v0, vcc, s22, v66
	v_cvt_pk_bf16_f32 v4, v53, s0
	s_nop 0
	v_addc_co_u32_e32 v1, vcc, 0, v67, vcc
	global_store_short v[0:1], v4, off
	v_cvt_pk_bf16_f32 v4, v54, s0
	global_store_short v[0:1], v4, off offset:256
	v_cvt_pk_bf16_f32 v4, v55, s0
	global_store_short v[0:1], v4, off offset:512
	v_cvt_pk_bf16_f32 v4, v56, s0
	global_store_short v[0:1], v4, off offset:768
	v_cvt_pk_bf16_f32 v4, v57, s0
	global_store_short v[0:1], v4, off offset:1024
	v_cvt_pk_bf16_f32 v4, v58, s0
	global_store_short v[0:1], v4, off offset:1280
	v_cvt_pk_bf16_f32 v4, v59, s0
	global_store_short v[0:1], v4, off offset:1536
	v_cvt_pk_bf16_f32 v4, v60, s0
	global_store_short v[0:1], v4, off offset:1792
	v_cvt_pk_bf16_f32 v4, v61, s0
	global_store_short v[0:1], v4, off offset:2048
	v_cvt_pk_bf16_f32 v4, v62, s0
	global_store_short v[0:1], v4, off offset:2304
	v_cvt_pk_bf16_f32 v4, v63, s0
	global_store_short v[0:1], v4, off offset:2560
	v_cvt_pk_bf16_f32 v4, v64, s0
	v_cvt_pk_bf16_f32 v2, v2, s0
	global_store_short v[0:1], v4, off offset:2816
	v_cvt_pk_bf16_f32 v4, v65, s0
	global_store_short v[0:1], v2, off offset:3328
	v_cvt_pk_bf16_f32 v2, v3, s0
	global_store_short v[0:1], v4, off offset:3072
	global_store_short v[0:1], v2, off offset:3584
